# rwkv mode-1 chunk scan rewritten (token loads prefetched one sub-block ahead, decay folded into operands, LDS reads 8 deep); mode-0 with decay folding
# speedup vs baseline: 1.0437x; 1.0304x over previous
; #define LAS __attribute__((address_space(3)))
; template <int MODE> __device__ __forceinline__ void rwkv_item(const Params& P, int e, int c, int h, LAS float* slab, int lane) {
;     ...
;     const float mu_r = P.in[I_AMU][(size_t)e * DINA + ch], mu_k = P.in[I_AMU][(size_t)e * DINA + 512 + ch];
;     const float kkw = P.in[I_AKK][e * 512 + ch], ka = P.in[I_AKA][e * 512 + ch], rk = P.in[I_ARK][e * 512 + ch];
;     const float lnw = P.in[I_ALNW][e * 512 + ch], lnb = P.in[I_ALNB][e * 512 + ch];
;     constexpr int SB = MODE == 0 ? 4 : 8;
;     f32x2 S2[32], C2[MODE == 0 ? 32 : 1];
;     const size_t rowoff = (((size_t)c * 8 + h) * 64 + lane) * 64;
;     if (MODE == 0) {
; #pragma unroll
;         for (int i = 0; i < 32; ++i) { S2[i] = (f32x2){(2 * i) == lane ? 1.f : 0.f, (2 * i + 1) == lane ? 1.f : 0.f}; C2[i] = (f32x2){0.f, 0.f}; }
;     } else {
; #pragma unroll
;         for (int q = 0; q < 16; ++q) { const f32x4 v = *(const f32x4*)(MCC + rowoff + 4 * q); S2[2 * q] = (f32x2){v.x, v.y}; S2[2 * q + 1] = (f32x2){v.z, v.w}; }
;     }
;     float r1[SB + 1], k1[SB + 1], vv[SB], dd[SB], aa[SB], gg[MODE == 1 ? SB : 1];
;     ...
;     if (MODE == 1) RW_LOAD(c * RLCH);
; template <int MODE> __device__ __forceinline__ void stage_rwkv_scan(const Params& P, int e, LAS unsigned char* lds) {
;     int tid = threadIdx.x; asm volatile("" : "+v"(tid)); const int lane = tid & 63, wave = __builtin_amdgcn_readfirstlane(tid >> 6);
;     LAS float* slab = (LAS float*)(lds + wave * 16384);
;     const int gw = blockIdx.x * NWAVES + wave, ngw = gridDim.x * NWAVES;
;     for (int it = gw; it < RNCH * 8; it += ngw) rwkv_item<MODE>(P, e, it >> 3, it & 7, slab, lane);
.LBB0_202:
	s_andn2_b64 vcc, exec, s[0:1]
	s_cbranch_vccnz .LBB0_213
	v_mov_b32_e32 v0, v211
	s_nop 0
	v_readfirstlane_b32 s0, v0
	s_ashr_i32 s0, s0, 6
	s_add_i32 s2, s0, s55
	s_cmpk_gt_i32 s2, 0x7ff
	s_cbranch_scc1 .LBB0_213
	s_lshl_b32 s0, s0, 14
	s_add_i32 s3, s0, 0
	s_load_dwordx2 s[0:1], s[30:31], 0x38
	s_load_dwordx8 s[12:19], s[30:31], 0x68
	s_load_dwordx2 s[8:9], s[30:31], 0x88
	s_waitcnt lgkmcnt(0)
	s_add_u32 s4, s72, 0xd880000
	s_addc_u32 s5, s73, 0
	s_add_u32 s6, s72, 0x12880000
	s_addc_u32 s7, s73, 0
	v_readlane_b32 s10, v255, 5
	s_add_u32 s26, s0, s10
	v_readlane_b32 s0, v255, 4
	s_addc_u32 s27, s1, s0
	s_add_u32 s46, s72, 0xb880000
	s_addc_u32 s47, s73, 0
	s_add_u32 s50, s72, 0xf880000
	s_addc_u32 s51, s73, 0
	v_readlane_b32 s0, v255, 3
	s_add_u32 s66, s72, s0
	s_addc_u32 s67, s73, 0
	s_add_u32 s70, s72, 0x10880000
	s_addc_u32 s71, s73, 0
	v_readlane_b32 s52, v254, 55
	v_readlane_b32 s53, v254, 56
	v_and_b32_e32 v64, 63, v0
	v_lshl_add_u32 v109, v64, 2, s3
	s_mov_b64 s[72:73], s[8:9]
.LBB0_205:
	s_and_b32 s0, s2, 7
	s_lshl_b32 s0, s0, 6
	v_readlane_b32 s1, v255, 8
	v_or_b32_e32 v114, s0, v64
	v_lshlrev_b32_e32 v115, 2, v114
	global_load_dword v111, v115, s[26:27]
	global_load_dword v116, v115, s[26:27] offset:2048
	v_or_b32_e32 v122, s1, v114
	v_lshlrev_b32_e32 v122, 2, v122
	global_load_dword v117, v122, s[12:13]
	global_load_dword v118, v122, s[14:15]
	global_load_dword v119, v122, s[16:17]
	global_load_dword v120, v122, s[18:19]
	global_load_dword v121, v122, s[72:73]
	s_lshl_b32 s0, s2, 6
	v_or_b32_e32 v123, s0, v64
	v_lshlrev_b32_e32 v123, 8, v123
	global_load_dwordx4 v[0:3], v123, s[6:7]
	global_load_dwordx4 v[4:7], v123, s[6:7] offset:16
	global_load_dwordx4 v[8:11], v123, s[6:7] offset:32
	global_load_dwordx4 v[12:15], v123, s[6:7] offset:48
	global_load_dwordx4 v[16:19], v123, s[6:7] offset:64
	global_load_dwordx4 v[20:23], v123, s[6:7] offset:80
	global_load_dwordx4 v[24:27], v123, s[6:7] offset:96
	global_load_dwordx4 v[28:31], v123, s[6:7] offset:112
	global_load_dwordx4 v[32:35], v123, s[6:7] offset:128
	global_load_dwordx4 v[36:39], v123, s[6:7] offset:144
	global_load_dwordx4 v[40:43], v123, s[6:7] offset:160
	global_load_dwordx4 v[44:47], v123, s[6:7] offset:176
	global_load_dwordx4 v[48:51], v123, s[6:7] offset:192
	global_load_dwordx4 v[52:55], v123, s[6:7] offset:208
	global_load_dwordx4 v[56:59], v123, s[6:7] offset:224
	global_load_dwordx4 v[60:63], v123, s[6:7] offset:240
	s_ashr_i32 s0, s2, 3
	s_lshl_b32 s1, s0, 6
	s_mul_i32 s8, s1, 0xe00
	v_lshl_add_u32 v108, v114, 1, s8
	s_lshl_b32 s8, s1, 10
	v_lshl_add_u32 v110, v114, 1, s8
	s_lshl_b32 s8, s1, 11
	v_lshl_add_u32 v112, v114, 2, s8
	v_lshl_add_u32 v113, v114, 1, s8
	s_cmp_eq_u32 s0, 0
	s_cselect_b32 s8, 0, 0xe00
	v_subrev_u32_e32 v115, s8, v108
	global_load_ushort v105, v115, s[52:53]
	global_load_ushort v106, v115, s[52:53] offset:1024
	global_load_ushort v65, v108, s[52:53]
	global_load_ushort v73, v108, s[52:53] offset:1024
	v_add_u32_e32 v115, 0xe00, v108
	global_load_ushort v66, v115, s[52:53]
	global_load_ushort v74, v115, s[52:53] offset:1024
	v_add_u32_e32 v122, 0x1c00, v108
	global_load_ushort v67, v122, s[52:53]
	global_load_ushort v75, v122, s[52:53] offset:1024
	v_add_u32_e32 v123, 0x2a00, v108
	global_load_ushort v68, v123, s[52:53]
	global_load_ushort v76, v123, s[52:53] offset:1024
	v_add_u32_e32 v114, 0x3800, v108
	global_load_ushort v69, v114, s[52:53]
	global_load_ushort v77, v114, s[52:53] offset:1024
	v_add_u32_e32 v115, 0x4600, v108
	global_load_ushort v70, v115, s[52:53]
	global_load_ushort v78, v115, s[52:53] offset:1024
	v_add_u32_e32 v122, 0x5400, v108
	global_load_ushort v71, v122, s[52:53]
	global_load_ushort v79, v122, s[52:53] offset:1024
	v_add_u32_e32 v123, 0x6200, v108
	global_load_ushort v72, v123, s[52:53]
	global_load_ushort v80, v123, s[52:53] offset:1024
	v_add_u32_e32 v114, 0x1000, v110
	global_load_ushort v81, v110, s[66:67]
	global_load_ushort v82, v110, s[66:67] offset:1024
	global_load_ushort v83, v110, s[66:67] offset:2048
	global_load_ushort v84, v110, s[66:67] offset:3072
	global_load_ushort v85, v114, s[66:67]
	global_load_ushort v86, v114, s[66:67] offset:1024
	global_load_ushort v87, v114, s[66:67] offset:2048
	global_load_ushort v88, v114, s[66:67] offset:3072
	global_load_ushort v97, v110, s[4:5]
	global_load_ushort v98, v110, s[4:5] offset:1024
	global_load_ushort v99, v110, s[4:5] offset:2048
	global_load_ushort v100, v110, s[4:5] offset:3072
	global_load_ushort v101, v114, s[4:5]
	global_load_ushort v102, v114, s[4:5] offset:1024
	global_load_ushort v103, v114, s[4:5] offset:2048
	global_load_ushort v104, v114, s[4:5] offset:3072
	global_load_ushort v167, v110, s[50:51]
	global_load_ushort v168, v110, s[50:51] offset:1024
	global_load_ushort v169, v110, s[50:51] offset:2048
	global_load_ushort v170, v110, s[50:51] offset:3072
	global_load_ushort v171, v114, s[50:51]
	global_load_ushort v172, v114, s[50:51] offset:1024
	global_load_ushort v173, v114, s[50:51] offset:2048
	global_load_ushort v174, v114, s[50:51] offset:3072
	v_add_u32_e32 v115, 0x1000, v112
	v_add_u32_e32 v122, 0x2000, v112
	v_add_u32_e32 v123, 0x3000, v112
	global_load_dword v89, v112, s[46:47]
	global_load_dword v90, v112, s[46:47] offset:2048
	global_load_dword v91, v115, s[46:47]
	global_load_dword v92, v115, s[46:47] offset:2048
	global_load_dword v93, v122, s[46:47]
	global_load_dword v94, v122, s[46:47] offset:2048
	global_load_dword v95, v123, s[46:47]
	global_load_dword v96, v123, s[46:47] offset:2048
	v_add_u32_e32 v108, 0x7000, v108
	v_add_u32_e32 v110, 0x2000, v110
	v_add_u32_e32 v112, 0x4000, v112
	v_mov_b32_e32 v107, 1.0
	s_cmp_gt_i32 s0, 0
	s_cselect_b64 vcc, -1, 0
	s_mov_b32 s1, 0
	s_waitcnt vmcnt(0)
	v_lshlrev_b32_e32 v105, 16, v105
	v_lshlrev_b32_e32 v106, 16, v106
	v_cndmask_b32_e32 v105, 0, v105, vcc
	v_cndmask_b32_e32 v106, 0, v106, vcc
	s_branch .Lm1_prep
; #define LAS __attribute__((address_space(3)))
; __device__ __forceinline__ float frsq(float x) { return __builtin_amdgcn_rsqf(x); }
; template <int MODE> __device__ __forceinline__ void rwkv_item(const Params& P, int e, int c, int h, LAS float* slab, int lane) {
;     ...
; #pragma unroll
;         for (int s = 0; s < SB; ++s) {
;             const float r = r1[s + 1] + (r1[s] - r1[s + 1]) * mu_r, k = k1[s + 1] + (k1[s] - k1[s + 1]) * mu_k, a = aa[s];
;             float kk = k * kkw;
;             const float ss = wave_sum(kk * kk);
;             kk *= frsq(fmaxf(ss, 1e-24f));
;             const float b = kk * a, kp = k * (1.f + (a - 1.f) * ka);
;             LAS float* st = slab + s * 512;
;             st[lane] = dd[s]; st[64 + lane] = kk; st[128 + lane] = b; st[192 + lane] = kp; st[256 + lane] = r; st[320 + lane] = vv[s];
;             if (MODE == 1) { st[384 + lane] = wave_sum(r * kp * rk); st[448 + lane] = gg[s]; }
;         }
.Lm1_sub:
	s_waitcnt vmcnt(8)
.Lm1_prep:
	v_lshlrev_b32_e32 v130, 16, v73
	v_lshlrev_b32_e32 v131, 16, v65
	v_sub_f32_e32 v124, v106, v130
	v_fma_f32 v124, v116, v124, v130
	v_mul_f32_e32 v125, v117, v124
	v_mul_f32_e32 v126, v125, v125
	v_lshlrev_b32_e32 v128, 16, v97
	v_lshlrev_b32_e32 v129, 16, v81
	v_mov_b32_dpp v126, v126 quad_perm:[1,0,3,2] row_mask:0xf bank_mask:0xf bound_ctrl:1
	v_fmac_f32_e32 v126, v125, v125
	v_sub_f32_e32 v132, v105, v131
	v_fma_f32 v132, v111, v132, v131
	v_add_f32_dpp v126, v126, v126 quad_perm:[2,3,0,1] row_mask:0xf bank_mask:0xf bound_ctrl:1
	s_nop 1
	v_add_f32_dpp v126, v126, v126 row_half_mirror row_mask:0xf bank_mask:0xf bound_ctrl:1
	s_nop 1
	v_add_f32_dpp v126, v126, v126 row_mirror row_mask:0xf bank_mask:0xf bound_ctrl:1
	s_nop 0
	v_readlane_b32 s8, v126, 16
	v_readlane_b32 s10, v126, 48
	v_readlane_b32 s0, v126, 0
	v_readlane_b32 s9, v126, 32
	v_mov_b32_e32 v126, s8
	v_mov_b32_e32 v127, s10
	v_add_f32_e32 v126, s0, v126
	v_add_f32_e32 v127, s9, v127
	v_add_f32_e32 v126, v126, v127
	v_max_f32_e32 v126, 0x179abe15, v126
	v_rsq_f32_e32 v126, v126
	v_add_f32_e32 v127, -1.0, v128
	v_fma_f32 v127, v118, v127, 1.0
	v_mul_f32_e32 v124, v124, v127
	v_mul_f32_e32 v125, v125, v126
	v_mul_f32_e32 v126, v128, v125
	v_mul_f32_e32 v133, v132, v124
	v_mul_f32_e32 v134, v119, v133
	v_mov_b32_e32 v106, v130
	v_mov_b32_e32 v105, v131
	v_mov_b32_dpp v134, v134 quad_perm:[1,0,3,2] row_mask:0xf bank_mask:0xf bound_ctrl:1
	v_fmac_f32_e32 v134, v119, v133
	v_mul_f32_e32 v125, v125, v107
	v_mul_f32_e32 v107, v107, v89
	v_add_f32_dpp v134, v134, v134 quad_perm:[2,3,0,1] row_mask:0xf bank_mask:0xf bound_ctrl:1
	s_nop 1
	v_add_f32_dpp v134, v134, v134 row_half_mirror row_mask:0xf bank_mask:0xf bound_ctrl:1
	s_nop 1
	v_add_f32_dpp v134, v134, v134 row_mirror row_mask:0xf bank_mask:0xf bound_ctrl:1
	s_nop 0
	v_readlane_b32 s8, v134, 16
	v_readlane_b32 s10, v134, 48
	v_readlane_b32 s0, v134, 0
	v_readlane_b32 s9, v134, 32
	v_mov_b32_e32 v134, s8
	v_mov_b32_e32 v127, s10
	v_add_f32_e32 v134, s0, v134
	v_add_f32_e32 v127, s9, v127
	v_add_f32_e32 v134, v134, v127
	v_rcp_f32_e32 v127, v107
	v_mul_f32_e32 v132, v132, v107
	v_lshlrev_b32_e32 v135, 16, v167
	v_mul_f32_e32 v126, v126, v127
	v_mul_f32_e32 v124, v124, v127
	ds_write2st64_b32 v109, v125, v126 offset0:1 offset1:2
	ds_write2st64_b32 v109, v124, v132 offset0:3 offset1:4
	ds_write2st64_b32 v109, v129, v134 offset0:5 offset1:6
	ds_write_b32 v109, v135 offset:1792
	v_lshlrev_b32_e32 v130, 16, v74
	v_lshlrev_b32_e32 v131, 16, v66
	v_sub_f32_e32 v124, v106, v130
	v_fma_f32 v124, v116, v124, v130
	v_mul_f32_e32 v125, v117, v124
	v_mul_f32_e32 v126, v125, v125
	v_lshlrev_b32_e32 v128, 16, v98
	v_lshlrev_b32_e32 v129, 16, v82
	v_mov_b32_dpp v126, v126 quad_perm:[1,0,3,2] row_mask:0xf bank_mask:0xf bound_ctrl:1
	v_fmac_f32_e32 v126, v125, v125
	v_sub_f32_e32 v132, v105, v131
	v_fma_f32 v132, v111, v132, v131
	v_add_f32_dpp v126, v126, v126 quad_perm:[2,3,0,1] row_mask:0xf bank_mask:0xf bound_ctrl:1
	s_nop 1
	v_add_f32_dpp v126, v126, v126 row_half_mirror row_mask:0xf bank_mask:0xf bound_ctrl:1
	s_nop 1
	v_add_f32_dpp v126, v126, v126 row_mirror row_mask:0xf bank_mask:0xf bound_ctrl:1
	s_nop 0
	v_readlane_b32 s8, v126, 16
	v_readlane_b32 s10, v126, 48
	v_readlane_b32 s0, v126, 0
	v_readlane_b32 s9, v126, 32
	v_mov_b32_e32 v126, s8
	v_mov_b32_e32 v127, s10
	v_add_f32_e32 v126, s0, v126
	v_add_f32_e32 v127, s9, v127
	v_add_f32_e32 v126, v126, v127
	v_max_f32_e32 v126, 0x179abe15, v126
	v_rsq_f32_e32 v126, v126
	v_add_f32_e32 v127, -1.0, v128
	v_fma_f32 v127, v118, v127, 1.0
	v_mul_f32_e32 v124, v124, v127
	v_mul_f32_e32 v125, v125, v126
	v_mul_f32_e32 v126, v128, v125
	v_mul_f32_e32 v133, v132, v124
	v_mul_f32_e32 v134, v119, v133
	v_mov_b32_e32 v106, v130
	v_mov_b32_e32 v105, v131
	v_mov_b32_dpp v134, v134 quad_perm:[1,0,3,2] row_mask:0xf bank_mask:0xf bound_ctrl:1
	v_fmac_f32_e32 v134, v119, v133
	v_mul_f32_e32 v125, v125, v107
	v_mul_f32_e32 v107, v107, v90
	v_add_f32_dpp v134, v134, v134 quad_perm:[2,3,0,1] row_mask:0xf bank_mask:0xf bound_ctrl:1
	s_nop 1
	v_add_f32_dpp v134, v134, v134 row_half_mirror row_mask:0xf bank_mask:0xf bound_ctrl:1
	s_nop 1
	v_add_f32_dpp v134, v134, v134 row_mirror row_mask:0xf bank_mask:0xf bound_ctrl:1
	s_nop 0
	v_readlane_b32 s8, v134, 16
	v_readlane_b32 s10, v134, 48
	v_readlane_b32 s0, v134, 0
	v_readlane_b32 s9, v134, 32
	v_mov_b32_e32 v134, s8
	v_mov_b32_e32 v127, s10
	v_add_f32_e32 v134, s0, v134
	v_add_f32_e32 v127, s9, v127
	v_add_f32_e32 v134, v134, v127
	v_rcp_f32_e32 v127, v107
	v_mul_f32_e32 v132, v132, v107
	v_lshlrev_b32_e32 v135, 16, v168
	v_mul_f32_e32 v126, v126, v127
	v_mul_f32_e32 v124, v124, v127
	ds_write2st64_b32 v109, v125, v126 offset0:9 offset1:10
	ds_write2st64_b32 v109, v124, v132 offset0:11 offset1:12
	ds_write2st64_b32 v109, v129, v134 offset0:13 offset1:14
	ds_write_b32 v109, v135 offset:3840
	v_lshlrev_b32_e32 v130, 16, v75
	v_lshlrev_b32_e32 v131, 16, v67
	v_sub_f32_e32 v124, v106, v130
	v_fma_f32 v124, v116, v124, v130
	v_mul_f32_e32 v125, v117, v124
	v_mul_f32_e32 v126, v125, v125
	v_lshlrev_b32_e32 v128, 16, v99
	v_lshlrev_b32_e32 v129, 16, v83
	v_mov_b32_dpp v126, v126 quad_perm:[1,0,3,2] row_mask:0xf bank_mask:0xf bound_ctrl:1
	v_fmac_f32_e32 v126, v125, v125
	v_sub_f32_e32 v132, v105, v131
	v_fma_f32 v132, v111, v132, v131
	v_add_f32_dpp v126, v126, v126 quad_perm:[2,3,0,1] row_mask:0xf bank_mask:0xf bound_ctrl:1
	s_nop 1
	v_add_f32_dpp v126, v126, v126 row_half_mirror row_mask:0xf bank_mask:0xf bound_ctrl:1
	s_nop 1
	v_add_f32_dpp v126, v126, v126 row_mirror row_mask:0xf bank_mask:0xf bound_ctrl:1
	s_nop 0
; #define LAS __attribute__((address_space(3)))
; __device__ __forceinline__ float frsq(float x) { return __builtin_amdgcn_rsqf(x); }
; template <int MODE> __device__ __forceinline__ void rwkv_item(const Params& P, int e, int c, int h, LAS float* slab, int lane) {
;     ...
; #pragma unroll
;         for (int s = 0; s < SB; ++s) {
;             const float r = r1[s + 1] + (r1[s] - r1[s + 1]) * mu_r, k = k1[s + 1] + (k1[s] - k1[s + 1]) * mu_k, a = aa[s];
;             float kk = k * kkw;
;             const float ss = wave_sum(kk * kk);
;             kk *= frsq(fmaxf(ss, 1e-24f));
;             const float b = kk * a, kp = k * (1.f + (a - 1.f) * ka);
;             LAS float* st = slab + s * 512;
;             st[lane] = dd[s]; st[64 + lane] = kk; st[128 + lane] = b; st[192 + lane] = kp; st[256 + lane] = r; st[320 + lane] = vv[s];
;             if (MODE == 1) { st[384 + lane] = wave_sum(r * kp * rk); st[448 + lane] = gg[s]; }
;         }
	v_readlane_b32 s8, v126, 16
	v_readlane_b32 s10, v126, 48
	v_readlane_b32 s0, v126, 0
	v_readlane_b32 s9, v126, 32
	v_mov_b32_e32 v126, s8
	v_mov_b32_e32 v127, s10
	v_add_f32_e32 v126, s0, v126
	v_add_f32_e32 v127, s9, v127
	v_add_f32_e32 v126, v126, v127
	v_max_f32_e32 v126, 0x179abe15, v126
	v_rsq_f32_e32 v126, v126
	v_add_f32_e32 v127, -1.0, v128
	v_fma_f32 v127, v118, v127, 1.0
	v_mul_f32_e32 v124, v124, v127
	v_mul_f32_e32 v125, v125, v126
	v_mul_f32_e32 v126, v128, v125
	v_mul_f32_e32 v133, v132, v124
	v_mul_f32_e32 v134, v119, v133
	v_mov_b32_e32 v106, v130
	v_mov_b32_e32 v105, v131
	v_mov_b32_dpp v134, v134 quad_perm:[1,0,3,2] row_mask:0xf bank_mask:0xf bound_ctrl:1
	v_fmac_f32_e32 v134, v119, v133
	v_mul_f32_e32 v125, v125, v107
	v_mul_f32_e32 v107, v107, v91
	v_add_f32_dpp v134, v134, v134 quad_perm:[2,3,0,1] row_mask:0xf bank_mask:0xf bound_ctrl:1
	s_nop 1
	v_add_f32_dpp v134, v134, v134 row_half_mirror row_mask:0xf bank_mask:0xf bound_ctrl:1
	s_nop 1
	v_add_f32_dpp v134, v134, v134 row_mirror row_mask:0xf bank_mask:0xf bound_ctrl:1
	s_nop 0
	v_readlane_b32 s8, v134, 16
	v_readlane_b32 s10, v134, 48
	v_readlane_b32 s0, v134, 0
	v_readlane_b32 s9, v134, 32
	v_mov_b32_e32 v134, s8
	v_mov_b32_e32 v127, s10
	v_add_f32_e32 v134, s0, v134
	v_add_f32_e32 v127, s9, v127
	v_add_f32_e32 v134, v134, v127
	v_rcp_f32_e32 v127, v107
	v_mul_f32_e32 v132, v132, v107
	v_lshlrev_b32_e32 v135, 16, v169
	v_mul_f32_e32 v126, v126, v127
	v_mul_f32_e32 v124, v124, v127
	ds_write2st64_b32 v109, v125, v126 offset0:17 offset1:18
	ds_write2st64_b32 v109, v124, v132 offset0:19 offset1:20
	ds_write2st64_b32 v109, v129, v134 offset0:21 offset1:22
	ds_write_b32 v109, v135 offset:5888
	v_lshlrev_b32_e32 v130, 16, v76
	v_lshlrev_b32_e32 v131, 16, v68
	v_sub_f32_e32 v124, v106, v130
	v_fma_f32 v124, v116, v124, v130
	v_mul_f32_e32 v125, v117, v124
	v_mul_f32_e32 v126, v125, v125
	v_lshlrev_b32_e32 v128, 16, v100
	v_lshlrev_b32_e32 v129, 16, v84
	v_mov_b32_dpp v126, v126 quad_perm:[1,0,3,2] row_mask:0xf bank_mask:0xf bound_ctrl:1
	v_fmac_f32_e32 v126, v125, v125
	v_sub_f32_e32 v132, v105, v131
	v_fma_f32 v132, v111, v132, v131
	v_add_f32_dpp v126, v126, v126 quad_perm:[2,3,0,1] row_mask:0xf bank_mask:0xf bound_ctrl:1
	s_nop 1
	v_add_f32_dpp v126, v126, v126 row_half_mirror row_mask:0xf bank_mask:0xf bound_ctrl:1
	s_nop 1
	v_add_f32_dpp v126, v126, v126 row_mirror row_mask:0xf bank_mask:0xf bound_ctrl:1
	s_nop 0
	v_readlane_b32 s8, v126, 16
	v_readlane_b32 s10, v126, 48
	v_readlane_b32 s0, v126, 0
	v_readlane_b32 s9, v126, 32
	v_mov_b32_e32 v126, s8
	v_mov_b32_e32 v127, s10
	v_add_f32_e32 v126, s0, v126
	v_add_f32_e32 v127, s9, v127
	v_add_f32_e32 v126, v126, v127
	v_max_f32_e32 v126, 0x179abe15, v126
	v_rsq_f32_e32 v126, v126
	v_add_f32_e32 v127, -1.0, v128
	v_fma_f32 v127, v118, v127, 1.0
	v_mul_f32_e32 v124, v124, v127
	v_mul_f32_e32 v125, v125, v126
	v_mul_f32_e32 v126, v128, v125
	v_mul_f32_e32 v133, v132, v124
	v_mul_f32_e32 v134, v119, v133
	v_mov_b32_e32 v106, v130
	v_mov_b32_e32 v105, v131
	v_mov_b32_dpp v134, v134 quad_perm:[1,0,3,2] row_mask:0xf bank_mask:0xf bound_ctrl:1
	v_fmac_f32_e32 v134, v119, v133
	v_mul_f32_e32 v125, v125, v107
	v_mul_f32_e32 v107, v107, v92
	v_add_f32_dpp v134, v134, v134 quad_perm:[2,3,0,1] row_mask:0xf bank_mask:0xf bound_ctrl:1
	s_nop 1
	v_add_f32_dpp v134, v134, v134 row_half_mirror row_mask:0xf bank_mask:0xf bound_ctrl:1
	s_nop 1
	v_add_f32_dpp v134, v134, v134 row_mirror row_mask:0xf bank_mask:0xf bound_ctrl:1
	s_nop 0
	v_readlane_b32 s8, v134, 16
	v_readlane_b32 s10, v134, 48
	v_readlane_b32 s0, v134, 0
	v_readlane_b32 s9, v134, 32
	v_mov_b32_e32 v134, s8
	v_mov_b32_e32 v127, s10
	v_add_f32_e32 v134, s0, v134
	v_add_f32_e32 v127, s9, v127
	v_add_f32_e32 v134, v134, v127
	v_rcp_f32_e32 v127, v107
	v_mul_f32_e32 v132, v132, v107
	v_lshlrev_b32_e32 v135, 16, v170
	v_mul_f32_e32 v126, v126, v127
	v_mul_f32_e32 v124, v124, v127
	ds_write2st64_b32 v109, v125, v126 offset0:25 offset1:26
	ds_write2st64_b32 v109, v124, v132 offset0:27 offset1:28
	ds_write2st64_b32 v109, v129, v134 offset0:29 offset1:30
	ds_write_b32 v109, v135 offset:7936
	v_lshlrev_b32_e32 v130, 16, v77
	v_lshlrev_b32_e32 v131, 16, v69
	v_sub_f32_e32 v124, v106, v130
	v_fma_f32 v124, v116, v124, v130
	v_mul_f32_e32 v125, v117, v124
	v_mul_f32_e32 v126, v125, v125
	v_lshlrev_b32_e32 v128, 16, v101
	v_lshlrev_b32_e32 v129, 16, v85
	v_mov_b32_dpp v126, v126 quad_perm:[1,0,3,2] row_mask:0xf bank_mask:0xf bound_ctrl:1
	v_fmac_f32_e32 v126, v125, v125
	v_sub_f32_e32 v132, v105, v131
	v_fma_f32 v132, v111, v132, v131
	v_add_f32_dpp v126, v126, v126 quad_perm:[2,3,0,1] row_mask:0xf bank_mask:0xf bound_ctrl:1
	s_nop 1
	v_add_f32_dpp v126, v126, v126 row_half_mirror row_mask:0xf bank_mask:0xf bound_ctrl:1
	s_nop 1
	v_add_f32_dpp v126, v126, v126 row_mirror row_mask:0xf bank_mask:0xf bound_ctrl:1
	s_nop 0
	v_readlane_b32 s8, v126, 16
	v_readlane_b32 s10, v126, 48
	v_readlane_b32 s0, v126, 0
	v_readlane_b32 s9, v126, 32
	v_mov_b32_e32 v126, s8
	v_mov_b32_e32 v127, s10
	v_add_f32_e32 v126, s0, v126
	v_add_f32_e32 v127, s9, v127
	v_add_f32_e32 v126, v126, v127
	v_max_f32_e32 v126, 0x179abe15, v126
	v_rsq_f32_e32 v126, v126
	v_add_f32_e32 v127, -1.0, v128
	v_fma_f32 v127, v118, v127, 1.0
	v_mul_f32_e32 v124, v124, v127
	v_mul_f32_e32 v125, v125, v126
	v_mul_f32_e32 v126, v128, v125
	v_mul_f32_e32 v133, v132, v124
	v_mul_f32_e32 v134, v119, v133
	v_mov_b32_e32 v106, v130
	v_mov_b32_e32 v105, v131
	v_mov_b32_dpp v134, v134 quad_perm:[1,0,3,2] row_mask:0xf bank_mask:0xf bound_ctrl:1
	v_fmac_f32_e32 v134, v119, v133
	v_mul_f32_e32 v125, v125, v107
	v_mul_f32_e32 v107, v107, v93
; #define LAS __attribute__((address_space(3)))
; __device__ __forceinline__ float frsq(float x) { return __builtin_amdgcn_rsqf(x); }
; template <int MODE> __device__ __forceinline__ void rwkv_item(const Params& P, int e, int c, int h, LAS float* slab, int lane) {
;     ...
; #pragma unroll
;         for (int s = 0; s < SB; ++s) {
;             const float r = r1[s + 1] + (r1[s] - r1[s + 1]) * mu_r, k = k1[s + 1] + (k1[s] - k1[s + 1]) * mu_k, a = aa[s];
;             float kk = k * kkw;
;             const float ss = wave_sum(kk * kk);
;             kk *= frsq(fmaxf(ss, 1e-24f));
;             const float b = kk * a, kp = k * (1.f + (a - 1.f) * ka);
;             LAS float* st = slab + s * 512;
;             st[lane] = dd[s]; st[64 + lane] = kk; st[128 + lane] = b; st[192 + lane] = kp; st[256 + lane] = r; st[320 + lane] = vv[s];
;             if (MODE == 1) { st[384 + lane] = wave_sum(r * kp * rk); st[448 + lane] = gg[s]; }
;         }
	v_add_f32_dpp v134, v134, v134 quad_perm:[2,3,0,1] row_mask:0xf bank_mask:0xf bound_ctrl:1
	s_nop 1
	v_add_f32_dpp v134, v134, v134 row_half_mirror row_mask:0xf bank_mask:0xf bound_ctrl:1
	s_nop 1
	v_add_f32_dpp v134, v134, v134 row_mirror row_mask:0xf bank_mask:0xf bound_ctrl:1
	s_nop 0
	v_readlane_b32 s8, v134, 16
	v_readlane_b32 s10, v134, 48
	v_readlane_b32 s0, v134, 0
	v_readlane_b32 s9, v134, 32
	v_mov_b32_e32 v134, s8
	v_mov_b32_e32 v127, s10
	v_add_f32_e32 v134, s0, v134
	v_add_f32_e32 v127, s9, v127
	v_add_f32_e32 v134, v134, v127
	v_rcp_f32_e32 v127, v107
	v_mul_f32_e32 v132, v132, v107
	v_lshlrev_b32_e32 v135, 16, v171
	v_mul_f32_e32 v126, v126, v127
	v_mul_f32_e32 v124, v124, v127
	ds_write2st64_b32 v109, v125, v126 offset0:33 offset1:34
	ds_write2st64_b32 v109, v124, v132 offset0:35 offset1:36
	ds_write2st64_b32 v109, v129, v134 offset0:37 offset1:38
	ds_write_b32 v109, v135 offset:9984
	v_lshlrev_b32_e32 v130, 16, v78
	v_lshlrev_b32_e32 v131, 16, v70
	v_sub_f32_e32 v124, v106, v130
	v_fma_f32 v124, v116, v124, v130
	v_mul_f32_e32 v125, v117, v124
	v_mul_f32_e32 v126, v125, v125
	v_lshlrev_b32_e32 v128, 16, v102
	v_lshlrev_b32_e32 v129, 16, v86
	v_mov_b32_dpp v126, v126 quad_perm:[1,0,3,2] row_mask:0xf bank_mask:0xf bound_ctrl:1
	v_fmac_f32_e32 v126, v125, v125
	v_sub_f32_e32 v132, v105, v131
	v_fma_f32 v132, v111, v132, v131
	v_add_f32_dpp v126, v126, v126 quad_perm:[2,3,0,1] row_mask:0xf bank_mask:0xf bound_ctrl:1
	s_nop 1
	v_add_f32_dpp v126, v126, v126 row_half_mirror row_mask:0xf bank_mask:0xf bound_ctrl:1
	s_nop 1
	v_add_f32_dpp v126, v126, v126 row_mirror row_mask:0xf bank_mask:0xf bound_ctrl:1
	s_nop 0
	v_readlane_b32 s8, v126, 16
	v_readlane_b32 s10, v126, 48
	v_readlane_b32 s0, v126, 0
	v_readlane_b32 s9, v126, 32
	v_mov_b32_e32 v126, s8
	v_mov_b32_e32 v127, s10
	v_add_f32_e32 v126, s0, v126
	v_add_f32_e32 v127, s9, v127
	v_add_f32_e32 v126, v126, v127
	v_max_f32_e32 v126, 0x179abe15, v126
	v_rsq_f32_e32 v126, v126
	v_add_f32_e32 v127, -1.0, v128
	v_fma_f32 v127, v118, v127, 1.0
	v_mul_f32_e32 v124, v124, v127
	v_mul_f32_e32 v125, v125, v126
	v_mul_f32_e32 v126, v128, v125
	v_mul_f32_e32 v133, v132, v124
	v_mul_f32_e32 v134, v119, v133
	v_mov_b32_e32 v106, v130
	v_mov_b32_e32 v105, v131
	v_mov_b32_dpp v134, v134 quad_perm:[1,0,3,2] row_mask:0xf bank_mask:0xf bound_ctrl:1
	v_fmac_f32_e32 v134, v119, v133
	v_mul_f32_e32 v125, v125, v107
	v_mul_f32_e32 v107, v107, v94
	v_add_f32_dpp v134, v134, v134 quad_perm:[2,3,0,1] row_mask:0xf bank_mask:0xf bound_ctrl:1
	s_nop 1
	v_add_f32_dpp v134, v134, v134 row_half_mirror row_mask:0xf bank_mask:0xf bound_ctrl:1
	s_nop 1
	v_add_f32_dpp v134, v134, v134 row_mirror row_mask:0xf bank_mask:0xf bound_ctrl:1
	s_nop 0
	v_readlane_b32 s8, v134, 16
	v_readlane_b32 s10, v134, 48
	v_readlane_b32 s0, v134, 0
	v_readlane_b32 s9, v134, 32
	v_mov_b32_e32 v134, s8
	v_mov_b32_e32 v127, s10
	v_add_f32_e32 v134, s0, v134
	v_add_f32_e32 v127, s9, v127
	v_add_f32_e32 v134, v134, v127
	v_rcp_f32_e32 v127, v107
	v_mul_f32_e32 v132, v132, v107
	v_lshlrev_b32_e32 v135, 16, v172
	v_mul_f32_e32 v126, v126, v127
	v_mul_f32_e32 v124, v124, v127
	ds_write2st64_b32 v109, v125, v126 offset0:41 offset1:42
	ds_write2st64_b32 v109, v124, v132 offset0:43 offset1:44
	ds_write2st64_b32 v109, v129, v134 offset0:45 offset1:46
	ds_write_b32 v109, v135 offset:12032
	v_lshlrev_b32_e32 v130, 16, v79
	v_lshlrev_b32_e32 v131, 16, v71
	v_sub_f32_e32 v124, v106, v130
	v_fma_f32 v124, v116, v124, v130
	v_mul_f32_e32 v125, v117, v124
	v_mul_f32_e32 v126, v125, v125
	v_lshlrev_b32_e32 v128, 16, v103
	v_lshlrev_b32_e32 v129, 16, v87
	v_mov_b32_dpp v126, v126 quad_perm:[1,0,3,2] row_mask:0xf bank_mask:0xf bound_ctrl:1
	v_fmac_f32_e32 v126, v125, v125
	v_sub_f32_e32 v132, v105, v131
	v_fma_f32 v132, v111, v132, v131
	v_add_f32_dpp v126, v126, v126 quad_perm:[2,3,0,1] row_mask:0xf bank_mask:0xf bound_ctrl:1
	s_nop 1
	v_add_f32_dpp v126, v126, v126 row_half_mirror row_mask:0xf bank_mask:0xf bound_ctrl:1
	s_nop 1
	v_add_f32_dpp v126, v126, v126 row_mirror row_mask:0xf bank_mask:0xf bound_ctrl:1
	s_nop 0
	v_readlane_b32 s8, v126, 16
	v_readlane_b32 s10, v126, 48
	v_readlane_b32 s0, v126, 0
	v_readlane_b32 s9, v126, 32
	v_mov_b32_e32 v126, s8
	v_mov_b32_e32 v127, s10
	v_add_f32_e32 v126, s0, v126
	v_add_f32_e32 v127, s9, v127
	v_add_f32_e32 v126, v126, v127
	v_max_f32_e32 v126, 0x179abe15, v126
	v_rsq_f32_e32 v126, v126
	v_add_f32_e32 v127, -1.0, v128
	v_fma_f32 v127, v118, v127, 1.0
	v_mul_f32_e32 v124, v124, v127
	v_mul_f32_e32 v125, v125, v126
	v_mul_f32_e32 v126, v128, v125
	v_mul_f32_e32 v133, v132, v124
	v_mul_f32_e32 v134, v119, v133
	v_mov_b32_e32 v106, v130
	v_mov_b32_e32 v105, v131
	v_mov_b32_dpp v134, v134 quad_perm:[1,0,3,2] row_mask:0xf bank_mask:0xf bound_ctrl:1
	v_fmac_f32_e32 v134, v119, v133
	v_mul_f32_e32 v125, v125, v107
	v_mul_f32_e32 v107, v107, v95
	v_add_f32_dpp v134, v134, v134 quad_perm:[2,3,0,1] row_mask:0xf bank_mask:0xf bound_ctrl:1
	s_nop 1
	v_add_f32_dpp v134, v134, v134 row_half_mirror row_mask:0xf bank_mask:0xf bound_ctrl:1
	s_nop 1
	v_add_f32_dpp v134, v134, v134 row_mirror row_mask:0xf bank_mask:0xf bound_ctrl:1
	s_nop 0
	v_readlane_b32 s8, v134, 16
	v_readlane_b32 s10, v134, 48
	v_readlane_b32 s0, v134, 0
	v_readlane_b32 s9, v134, 32
	v_mov_b32_e32 v134, s8
	v_mov_b32_e32 v127, s10
	v_add_f32_e32 v134, s0, v134
	v_add_f32_e32 v127, s9, v127
	v_add_f32_e32 v134, v134, v127
	v_rcp_f32_e32 v127, v107
	v_mul_f32_e32 v132, v132, v107
	v_lshlrev_b32_e32 v135, 16, v173
	v_mul_f32_e32 v126, v126, v127
	v_mul_f32_e32 v124, v124, v127
	ds_write2st64_b32 v109, v125, v126 offset0:49 offset1:50
; #define LAS __attribute__((address_space(3)))
; __device__ __forceinline__ float frsq(float x) { return __builtin_amdgcn_rsqf(x); }
; #define LDS_WAIT() asm volatile("s_waitcnt lgkmcnt(0)" ::: "memory")
; template <int MODE> __device__ __forceinline__ void rwkv_item(const Params& P, int e, int c, int h, LAS float* slab, int lane) {
;     ...
; #pragma unroll
;         for (int s = 0; s < SB; ++s) {
;             const float r = r1[s + 1] + (r1[s] - r1[s + 1]) * mu_r, k = k1[s + 1] + (k1[s] - k1[s + 1]) * mu_k, a = aa[s];
;             float kk = k * kkw;
;             const float ss = wave_sum(kk * kk);
;             kk *= frsq(fmaxf(ss, 1e-24f));
;             const float b = kk * a, kp = k * (1.f + (a - 1.f) * ka);
;             LAS float* st = slab + s * 512;
;             st[lane] = dd[s]; st[64 + lane] = kk; st[128 + lane] = b; st[192 + lane] = kp; st[256 + lane] = r; st[320 + lane] = vv[s];
;             if (MODE == 1) { st[384 + lane] = wave_sum(r * kp * rk); st[448 + lane] = gg[s]; }
;         }
;         LDS_WAIT();
;         if (MODE == 1 && sb + 1 < RLCH / SB) RW_LOAD(tb + SB);
	ds_write2st64_b32 v109, v124, v132 offset0:51 offset1:52
	ds_write2st64_b32 v109, v129, v134 offset0:53 offset1:54
	ds_write_b32 v109, v135 offset:14080
	v_lshlrev_b32_e32 v130, 16, v80
	v_lshlrev_b32_e32 v131, 16, v72
	v_sub_f32_e32 v124, v106, v130
	v_fma_f32 v124, v116, v124, v130
	v_mul_f32_e32 v125, v117, v124
	v_mul_f32_e32 v126, v125, v125
	v_lshlrev_b32_e32 v128, 16, v104
	v_lshlrev_b32_e32 v129, 16, v88
	v_mov_b32_dpp v126, v126 quad_perm:[1,0,3,2] row_mask:0xf bank_mask:0xf bound_ctrl:1
	v_fmac_f32_e32 v126, v125, v125
	v_sub_f32_e32 v132, v105, v131
	v_fma_f32 v132, v111, v132, v131
	v_add_f32_dpp v126, v126, v126 quad_perm:[2,3,0,1] row_mask:0xf bank_mask:0xf bound_ctrl:1
	s_nop 1
	v_add_f32_dpp v126, v126, v126 row_half_mirror row_mask:0xf bank_mask:0xf bound_ctrl:1
	s_nop 1
	v_add_f32_dpp v126, v126, v126 row_mirror row_mask:0xf bank_mask:0xf bound_ctrl:1
	s_nop 0
	v_readlane_b32 s8, v126, 16
	v_readlane_b32 s10, v126, 48
	v_readlane_b32 s0, v126, 0
	v_readlane_b32 s9, v126, 32
	v_mov_b32_e32 v126, s8
	v_mov_b32_e32 v127, s10
	v_add_f32_e32 v126, s0, v126
	v_add_f32_e32 v127, s9, v127
	v_add_f32_e32 v126, v126, v127
	v_max_f32_e32 v126, 0x179abe15, v126
	v_rsq_f32_e32 v126, v126
	v_add_f32_e32 v127, -1.0, v128
	v_fma_f32 v127, v118, v127, 1.0
	v_mul_f32_e32 v124, v124, v127
	v_mul_f32_e32 v125, v125, v126
	v_mul_f32_e32 v126, v128, v125
	v_mul_f32_e32 v133, v132, v124
	v_mul_f32_e32 v134, v119, v133
	v_mov_b32_e32 v106, v130
	v_mov_b32_e32 v105, v131
	v_mov_b32_dpp v134, v134 quad_perm:[1,0,3,2] row_mask:0xf bank_mask:0xf bound_ctrl:1
	v_fmac_f32_e32 v134, v119, v133
	v_mul_f32_e32 v125, v125, v107
	v_mul_f32_e32 v107, v107, v96
	v_add_f32_dpp v134, v134, v134 quad_perm:[2,3,0,1] row_mask:0xf bank_mask:0xf bound_ctrl:1
	s_nop 1
	v_add_f32_dpp v134, v134, v134 row_half_mirror row_mask:0xf bank_mask:0xf bound_ctrl:1
	s_nop 1
	v_add_f32_dpp v134, v134, v134 row_mirror row_mask:0xf bank_mask:0xf bound_ctrl:1
	s_nop 0
	v_readlane_b32 s8, v134, 16
	v_readlane_b32 s10, v134, 48
	v_readlane_b32 s0, v134, 0
	v_readlane_b32 s9, v134, 32
	v_mov_b32_e32 v134, s8
	v_mov_b32_e32 v127, s10
	v_add_f32_e32 v134, s0, v134
	v_add_f32_e32 v127, s9, v127
	v_add_f32_e32 v134, v134, v127
	v_rcp_f32_e32 v127, v107
	v_mul_f32_e32 v132, v132, v107
	v_lshlrev_b32_e32 v135, 16, v174
	v_mul_f32_e32 v126, v126, v127
	v_mul_f32_e32 v124, v124, v127
	ds_write2st64_b32 v109, v125, v126 offset0:57 offset1:58
	ds_write2st64_b32 v109, v124, v132 offset0:59 offset1:60
	ds_write2st64_b32 v109, v129, v134 offset0:61 offset1:62
	ds_write_b32 v109, v135 offset:16128
	s_cmp_eq_u32 s1, 7
	s_cbranch_scc1 .Lm1_noload
	global_load_ushort v65, v108, s[52:53]
	global_load_ushort v73, v108, s[52:53] offset:1024
	v_add_u32_e32 v115, 0xe00, v108
	global_load_ushort v66, v115, s[52:53]
	global_load_ushort v74, v115, s[52:53] offset:1024
	v_add_u32_e32 v122, 0x1c00, v108
	global_load_ushort v67, v122, s[52:53]
	global_load_ushort v75, v122, s[52:53] offset:1024
	v_add_u32_e32 v123, 0x2a00, v108
	global_load_ushort v68, v123, s[52:53]
	global_load_ushort v76, v123, s[52:53] offset:1024
	v_add_u32_e32 v114, 0x3800, v108
	global_load_ushort v69, v114, s[52:53]
	global_load_ushort v77, v114, s[52:53] offset:1024
	v_add_u32_e32 v115, 0x4600, v108
	global_load_ushort v70, v115, s[52:53]
	global_load_ushort v78, v115, s[52:53] offset:1024
	v_add_u32_e32 v122, 0x5400, v108
	global_load_ushort v71, v122, s[52:53]
	global_load_ushort v79, v122, s[52:53] offset:1024
	v_add_u32_e32 v123, 0x6200, v108
	global_load_ushort v72, v123, s[52:53]
	global_load_ushort v80, v123, s[52:53] offset:1024
	v_add_u32_e32 v114, 0x1000, v110
	global_load_ushort v81, v110, s[66:67]
	global_load_ushort v82, v110, s[66:67] offset:1024
	global_load_ushort v83, v110, s[66:67] offset:2048
	global_load_ushort v84, v110, s[66:67] offset:3072
	global_load_ushort v85, v114, s[66:67]
	global_load_ushort v86, v114, s[66:67] offset:1024
	global_load_ushort v87, v114, s[66:67] offset:2048
	global_load_ushort v88, v114, s[66:67] offset:3072
	global_load_ushort v97, v110, s[4:5]
	global_load_ushort v98, v110, s[4:5] offset:1024
	global_load_ushort v99, v110, s[4:5] offset:2048
	global_load_ushort v100, v110, s[4:5] offset:3072
	global_load_ushort v101, v114, s[4:5]
	global_load_ushort v102, v114, s[4:5] offset:1024
	global_load_ushort v103, v114, s[4:5] offset:2048
	global_load_ushort v104, v114, s[4:5] offset:3072
	global_load_ushort v167, v110, s[50:51]
	global_load_ushort v168, v110, s[50:51] offset:1024
	global_load_ushort v169, v110, s[50:51] offset:2048
	global_load_ushort v170, v110, s[50:51] offset:3072
	global_load_ushort v171, v114, s[50:51]
	global_load_ushort v172, v114, s[50:51] offset:1024
	global_load_ushort v173, v114, s[50:51] offset:2048
	global_load_ushort v174, v114, s[50:51] offset:3072
	v_add_u32_e32 v115, 0x1000, v112
	v_add_u32_e32 v122, 0x2000, v112
	v_add_u32_e32 v123, 0x3000, v112
	global_load_dword v89, v112, s[46:47]
	global_load_dword v90, v112, s[46:47] offset:2048
	global_load_dword v91, v115, s[46:47]
	global_load_dword v92, v115, s[46:47] offset:2048
	global_load_dword v93, v122, s[46:47]
	global_load_dword v94, v122, s[46:47] offset:2048
	global_load_dword v95, v123, s[46:47]
	global_load_dword v96, v123, s[46:47] offset:2048
	v_add_u32_e32 v108, 0x7000, v108
	v_add_u32_e32 v110, 0x2000, v110
	v_add_u32_e32 v112, 0x4000, v112
.Lm1_noload:
	s_waitcnt lgkmcnt(0)
	s_mov_b32 s11, 0
; #define LAS __attribute__((address_space(3)))
; template <int MODE> __device__ __forceinline__ void rwkv_item(const Params& P, int e, int c, int h, LAS float* slab, int lane) {
;     ...
;         for (int s = 0; s < SB; ++s) {
;             const LAS float* st = slab + s * 512;
;             f32x2 aS0 = {0.f, 0.f}, aS1 = {0.f, 0.f}, aC0 = {0.f, 0.f}, aC1 = {0.f, 0.f};
;             constexpr int DB = 4, UB = 2;
;             constexpr int NDB = 16 / DB, NUB = 16 / UB;
;             constexpr int NB = MODE == 1 ? 2 : 1;
;             f32x4 kd[NB][DB];
;             f32x4 wq[NB][UB], bq[NB][UB], kq[NB][UB], rq[NB][MODE == 1 ? UB : 1];
;     ...
;             if (NB == 2) RW_LD_DOT(0, 0);
;             const float v = st[320 + lane];
; #pragma unroll
;             for (int hb = 0; hb < NDB; ++hb) {
;                 if (NB == 2) { if (hb + 1 < NDB) RW_LD_DOT((hb + 1) & 1, hb + 1); else RW_LD_UPD(0, 0); } else RW_LD_DOT(0, hb);
;                 __builtin_amdgcn_sched_barrier(0);
; #pragma unroll
;                 for (int q = 0; q < DB; ++q) {
;                     const int qq = DB * hb + q; const f32x4 k4 = kd[hb & (NB - 1)][q];
;                     aS0 += S2[2 * qq] * (f32x2){k4.x, k4.y}; aS1 += S2[2 * qq + 1] * (f32x2){k4.z, k4.w};
;                     if (MODE == 0) { aC0 += C2[2 * qq] * (f32x2){k4.x, k4.y}; aC1 += C2[2 * qq + 1] * (f32x2){k4.z, k4.w}; }
;                 }
;                 __builtin_amdgcn_sched_barrier(0);
;             }
;             const float nsk = -((aS0.x + aS0.y) + (aS1.x + aS1.y));
;             const float nskC = -((aC0.x + aC0.y) + (aC1.x + aC1.y));
;             f32x2 y0 = {0.f, 0.f}, y1 = {0.f, 0.f};
; #pragma unroll
;             for (int qb = 0; qb < NUB; ++qb) {
;                 if (NB == 2) { if (qb + 1 < NUB) RW_LD_UPD((qb + 1) & 1, qb + 1); } else RW_LD_UPD(0, qb);
;                 __builtin_amdgcn_sched_barrier(0);
; #pragma unroll
;                 for (int q = 0; q < UB; ++q) {
;                     const int qq = UB * qb + q;
;                     const f32x4 w4 = wq[qb & (NB - 1)][q], b4 = bq[qb & (NB - 1)][q], k4 = kq[qb & (NB - 1)][q];
;                     if (MODE == 0) {
;                         S2[2 * qq] = S2[2 * qq] * (f32x2){w4.x, w4.y} + (f32x2){b4.x, b4.y} * nsk;
;                         S2[2 * qq + 1] = S2[2 * qq + 1] * (f32x2){w4.z, w4.w} + (f32x2){b4.z, b4.w} * nsk;
.Lm1_step:
	s_add_i32 s8, s3, s11
	v_add_u32_e32 v197, s11, v109
	v_mov_b32_e32 v196, s8
	ds_read_b32 v194, v197 offset:1280
	ds_read_b128 v[136:139], v196 offset:256
	ds_read_b128 v[140:143], v196 offset:272
	ds_read_b128 v[144:147], v196 offset:288
	ds_read_b128 v[148:151], v196 offset:304
	ds_read_b128 v[176:179], v196 offset:320
	ds_read_b128 v[180:183], v196 offset:336
	ds_read_b128 v[184:187], v196 offset:352
	ds_read_b128 v[188:191], v196 offset:368
	s_waitcnt lgkmcnt(7)
	v_pk_fma_f32 v[158:159], v[0:1], v[136:137], 0 op_sel_hi:[1,1,0]
	v_pk_fma_f32 v[160:161], v[2:3], v[138:139], 0 op_sel_hi:[1,1,0]
	ds_read_b128 v[136:139], v196 offset:384
	s_waitcnt lgkmcnt(7)
	v_pk_fma_f32 v[158:159], v[4:5], v[140:141], v[158:159]
	v_pk_fma_f32 v[160:161], v[6:7], v[142:143], v[160:161]
	ds_read_b128 v[140:143], v196 offset:400
	s_waitcnt lgkmcnt(7)
	v_pk_fma_f32 v[158:159], v[8:9], v[144:145], v[158:159]
	v_pk_fma_f32 v[160:161], v[10:11], v[146:147], v[160:161]
	ds_read_b128 v[144:147], v196 offset:416
	s_waitcnt lgkmcnt(7)
	v_pk_fma_f32 v[158:159], v[12:13], v[148:149], v[158:159]
	v_pk_fma_f32 v[160:161], v[14:15], v[150:151], v[160:161]
	ds_read_b128 v[148:151], v196 offset:432
	s_waitcnt lgkmcnt(7)
	v_pk_fma_f32 v[158:159], v[16:17], v[176:177], v[158:159]
	v_pk_fma_f32 v[160:161], v[18:19], v[178:179], v[160:161]
	ds_read_b128 v[176:179], v196 offset:448
	s_waitcnt lgkmcnt(7)
	v_pk_fma_f32 v[158:159], v[20:21], v[180:181], v[158:159]
	v_pk_fma_f32 v[160:161], v[22:23], v[182:183], v[160:161]
	ds_read_b128 v[180:183], v196 offset:464
	s_waitcnt lgkmcnt(7)
	v_pk_fma_f32 v[158:159], v[24:25], v[184:185], v[158:159]
	v_pk_fma_f32 v[160:161], v[26:27], v[186:187], v[160:161]
	ds_read_b128 v[184:187], v196 offset:480
	s_waitcnt lgkmcnt(7)
	v_pk_fma_f32 v[158:159], v[28:29], v[188:189], v[158:159]
	v_pk_fma_f32 v[160:161], v[30:31], v[190:191], v[160:161]
	ds_read_b128 v[188:191], v196 offset:496
	s_waitcnt lgkmcnt(7)
	v_pk_fma_f32 v[158:159], v[32:33], v[136:137], v[158:159]
	v_pk_fma_f32 v[160:161], v[34:35], v[138:139], v[160:161]
	ds_read_b128 v[136:139], v196 offset:512
	s_waitcnt lgkmcnt(7)
	v_pk_fma_f32 v[158:159], v[36:37], v[140:141], v[158:159]
	v_pk_fma_f32 v[160:161], v[38:39], v[142:143], v[160:161]
	ds_read_b128 v[140:143], v196 offset:768
	s_waitcnt lgkmcnt(7)
	v_pk_fma_f32 v[158:159], v[40:41], v[144:145], v[158:159]
	v_pk_fma_f32 v[160:161], v[42:43], v[146:147], v[160:161]
	ds_read_b128 v[144:147], v196 offset:1024
	s_waitcnt lgkmcnt(7)
	v_pk_fma_f32 v[158:159], v[44:45], v[148:149], v[158:159]
	v_pk_fma_f32 v[160:161], v[46:47], v[150:151], v[160:161]
	ds_read_b128 v[148:151], v196 offset:528
	s_waitcnt lgkmcnt(7)
	v_pk_fma_f32 v[158:159], v[48:49], v[176:177], v[158:159]
	v_pk_fma_f32 v[160:161], v[50:51], v[178:179], v[160:161]
	ds_read_b128 v[176:179], v196 offset:784
	s_waitcnt lgkmcnt(7)
	v_pk_fma_f32 v[158:159], v[52:53], v[180:181], v[158:159]
	v_pk_fma_f32 v[160:161], v[54:55], v[182:183], v[160:161]
	ds_read_b128 v[180:183], v196 offset:1040
	s_waitcnt lgkmcnt(7)
	v_pk_fma_f32 v[158:159], v[56:57], v[184:185], v[158:159]
	v_pk_fma_f32 v[160:161], v[58:59], v[186:187], v[160:161]
	ds_read_b128 v[184:187], v196 offset:544
	s_waitcnt lgkmcnt(7)
	v_pk_fma_f32 v[158:159], v[60:61], v[188:189], v[158:159]
	v_pk_fma_f32 v[160:161], v[62:63], v[190:191], v[160:161]
	ds_read_b128 v[188:191], v196 offset:800
	v_add_f32_e32 v192, v158, v159
	v_add_f32_e32 v198, v160, v161
	v_add_f32_e32 v192, v198, v192
	s_waitcnt lgkmcnt(7)
	v_pk_fma_f32 v[0:1], v[136:137], v[192:193], v[0:1] op_sel_hi:[1,0,1] neg_lo:[0,1,0] neg_hi:[0,1,0]
	v_pk_fma_f32 v[2:3], v[138:139], v[192:193], v[2:3] op_sel_hi:[1,0,1] neg_lo:[0,1,0] neg_hi:[0,1,0]
	ds_read_b128 v[136:139], v196 offset:1056
	s_waitcnt lgkmcnt(7)
	v_pk_fma_f32 v[0:1], v[194:195], v[140:141], v[0:1] op_sel_hi:[0,1,1]
	v_pk_fma_f32 v[2:3], v[194:195], v[142:143], v[2:3] op_sel_hi:[0,1,1]
	ds_read_b128 v[140:143], v196 offset:560
	s_waitcnt lgkmcnt(7)
	v_pk_fma_f32 v[162:163], v[144:145], v[0:1], 0 op_sel_hi:[1,1,0]
	v_pk_fma_f32 v[164:165], v[146:147], v[2:3], 0 op_sel_hi:[1,1,0]
	ds_read_b128 v[144:147], v196 offset:816
	s_waitcnt lgkmcnt(7)
	v_pk_fma_f32 v[4:5], v[148:149], v[192:193], v[4:5] op_sel_hi:[1,0,1] neg_lo:[0,1,0] neg_hi:[0,1,0]
	v_pk_fma_f32 v[6:7], v[150:151], v[192:193], v[6:7] op_sel_hi:[1,0,1] neg_lo:[0,1,0] neg_hi:[0,1,0]
	ds_read_b128 v[148:151], v196 offset:1072
	s_waitcnt lgkmcnt(7)
	v_pk_fma_f32 v[4:5], v[194:195], v[176:177], v[4:5] op_sel_hi:[0,1,1]
	v_pk_fma_f32 v[6:7], v[194:195], v[178:179], v[6:7] op_sel_hi:[0,1,1]
	ds_read_b128 v[176:179], v196 offset:576
	s_waitcnt lgkmcnt(7)
	v_pk_fma_f32 v[162:163], v[180:181], v[4:5], v[162:163]
	v_pk_fma_f32 v[164:165], v[182:183], v[6:7], v[164:165]
	ds_read_b128 v[180:183], v196 offset:832
	s_waitcnt lgkmcnt(7)
	v_pk_fma_f32 v[8:9], v[184:185], v[192:193], v[8:9] op_sel_hi:[1,0,1] neg_lo:[0,1,0] neg_hi:[0,1,0]
	v_pk_fma_f32 v[10:11], v[186:187], v[192:193], v[10:11] op_sel_hi:[1,0,1] neg_lo:[0,1,0] neg_hi:[0,1,0]
	ds_read_b128 v[184:187], v196 offset:1088
	s_waitcnt lgkmcnt(7)
	v_pk_fma_f32 v[8:9], v[194:195], v[188:189], v[8:9] op_sel_hi:[0,1,1]
	v_pk_fma_f32 v[10:11], v[194:195], v[190:191], v[10:11] op_sel_hi:[0,1,1]
	ds_read_b128 v[188:191], v196 offset:592
	s_waitcnt lgkmcnt(7)
	v_pk_fma_f32 v[162:163], v[136:137], v[8:9], v[162:163]
	v_pk_fma_f32 v[164:165], v[138:139], v[10:11], v[164:165]
	ds_read_b128 v[136:139], v196 offset:848
	s_waitcnt lgkmcnt(7)
	v_pk_fma_f32 v[12:13], v[140:141], v[192:193], v[12:13] op_sel_hi:[1,0,1] neg_lo:[0,1,0] neg_hi:[0,1,0]
	v_pk_fma_f32 v[14:15], v[142:143], v[192:193], v[14:15] op_sel_hi:[1,0,1] neg_lo:[0,1,0] neg_hi:[0,1,0]
	ds_read_b128 v[140:143], v196 offset:1104
	s_waitcnt lgkmcnt(7)
; #define RW_LD_UPD(buf, qb) do { _Pragma("unroll") for (int q_ = 0; q_ < UB; ++q_) { const int qq_ = UB * (qb) + q_; \
;                 wq[buf][q_] = *(const LAS f32x4*)(st + 4 * qq_); bq[buf][q_] = *(const LAS f32x4*)(st + 128 + 4 * qq_); kq[buf][q_] = *(const LAS f32x4*)(st + 192 + 4 * qq_); \
;                 if (MODE == 1) rq[buf][q_] = *(const LAS f32x4*)(st + 256 + 4 * qq_); } } while (0)
; template <int MODE> __device__ __forceinline__ void rwkv_item(const Params& P, int e, int c, int h, LAS float* slab, int lane) {
;     ...
;             f32x2 y0 = {0.f, 0.f}, y1 = {0.f, 0.f};
; #pragma unroll
;             for (int qb = 0; qb < NUB; ++qb) {
;                 if (NB == 2) { if (qb + 1 < NUB) RW_LD_UPD((qb + 1) & 1, qb + 1); } else RW_LD_UPD(0, qb);
;                 __builtin_amdgcn_sched_barrier(0);
; #pragma unroll
;                 for (int q = 0; q < UB; ++q) {
;                     const int qq = UB * qb + q;
;                     const f32x4 w4 = wq[qb & (NB - 1)][q], b4 = bq[qb & (NB - 1)][q], k4 = kq[qb & (NB - 1)][q];
;                     if (MODE == 0) {
;                         S2[2 * qq] = S2[2 * qq] * (f32x2){w4.x, w4.y} + (f32x2){b4.x, b4.y} * nsk;
;                         S2[2 * qq + 1] = S2[2 * qq + 1] * (f32x2){w4.z, w4.w} + (f32x2){b4.z, b4.w} * nsk;
;                         C2[2 * qq] = C2[2 * qq] * (f32x2){w4.x, w4.y} + (f32x2){b4.x, b4.y} * nskC + (f32x2){k4.x, k4.y} * v;
;                         C2[2 * qq + 1] = C2[2 * qq + 1] * (f32x2){w4.z, w4.w} + (f32x2){b4.z, b4.w} * nskC + (f32x2){k4.z, k4.w} * v;
;                     } else {
;                         S2[2 * qq] = S2[2 * qq] * (f32x2){w4.x, w4.y} + (f32x2){b4.x, b4.y} * nsk + (f32x2){k4.x, k4.y} * v;
;                         S2[2 * qq + 1] = S2[2 * qq + 1] * (f32x2){w4.z, w4.w} + (f32x2){b4.z, b4.w} * nsk + (f32x2){k4.z, k4.w} * v;
;                         const f32x4 r4 = rq[qb & (NB - 1)][q]; y0 += S2[2 * qq] * (f32x2){r4.x, r4.y}; y1 += S2[2 * qq + 1] * (f32x2){r4.z, r4.w};
;                     }
;                 }
;                 __builtin_amdgcn_sched_barrier(0);
;             }
	v_pk_fma_f32 v[12:13], v[194:195], v[144:145], v[12:13] op_sel_hi:[0,1,1]
	v_pk_fma_f32 v[14:15], v[194:195], v[146:147], v[14:15] op_sel_hi:[0,1,1]
	ds_read_b128 v[144:147], v196 offset:608
	s_waitcnt lgkmcnt(7)
	v_pk_fma_f32 v[162:163], v[148:149], v[12:13], v[162:163]
	v_pk_fma_f32 v[164:165], v[150:151], v[14:15], v[164:165]
	ds_read_b128 v[148:151], v196 offset:864
	s_waitcnt lgkmcnt(7)
	v_pk_fma_f32 v[16:17], v[176:177], v[192:193], v[16:17] op_sel_hi:[1,0,1] neg_lo:[0,1,0] neg_hi:[0,1,0]
	v_pk_fma_f32 v[18:19], v[178:179], v[192:193], v[18:19] op_sel_hi:[1,0,1] neg_lo:[0,1,0] neg_hi:[0,1,0]
	ds_read_b128 v[176:179], v196 offset:1120
	s_waitcnt lgkmcnt(7)
	v_pk_fma_f32 v[16:17], v[194:195], v[180:181], v[16:17] op_sel_hi:[0,1,1]
	v_pk_fma_f32 v[18:19], v[194:195], v[182:183], v[18:19] op_sel_hi:[0,1,1]
	ds_read_b128 v[180:183], v196 offset:624
	s_waitcnt lgkmcnt(7)
	v_pk_fma_f32 v[162:163], v[184:185], v[16:17], v[162:163]
	v_pk_fma_f32 v[164:165], v[186:187], v[18:19], v[164:165]
	ds_read_b128 v[184:187], v196 offset:880
	s_waitcnt lgkmcnt(7)
	v_pk_fma_f32 v[20:21], v[188:189], v[192:193], v[20:21] op_sel_hi:[1,0,1] neg_lo:[0,1,0] neg_hi:[0,1,0]
	v_pk_fma_f32 v[22:23], v[190:191], v[192:193], v[22:23] op_sel_hi:[1,0,1] neg_lo:[0,1,0] neg_hi:[0,1,0]
	ds_read_b128 v[188:191], v196 offset:1136
	s_waitcnt lgkmcnt(7)
	v_pk_fma_f32 v[20:21], v[194:195], v[136:137], v[20:21] op_sel_hi:[0,1,1]
	v_pk_fma_f32 v[22:23], v[194:195], v[138:139], v[22:23] op_sel_hi:[0,1,1]
	ds_read_b128 v[136:139], v196 offset:640
	s_waitcnt lgkmcnt(7)
	v_pk_fma_f32 v[162:163], v[140:141], v[20:21], v[162:163]
	v_pk_fma_f32 v[164:165], v[142:143], v[22:23], v[164:165]
	ds_read_b128 v[140:143], v196 offset:896
	s_waitcnt lgkmcnt(7)
	v_pk_fma_f32 v[24:25], v[144:145], v[192:193], v[24:25] op_sel_hi:[1,0,1] neg_lo:[0,1,0] neg_hi:[0,1,0]
	v_pk_fma_f32 v[26:27], v[146:147], v[192:193], v[26:27] op_sel_hi:[1,0,1] neg_lo:[0,1,0] neg_hi:[0,1,0]
	ds_read_b128 v[144:147], v196 offset:1152
	s_waitcnt lgkmcnt(7)
	v_pk_fma_f32 v[24:25], v[194:195], v[148:149], v[24:25] op_sel_hi:[0,1,1]
	v_pk_fma_f32 v[26:27], v[194:195], v[150:151], v[26:27] op_sel_hi:[0,1,1]
	ds_read_b128 v[148:151], v196 offset:656
	s_waitcnt lgkmcnt(7)
	v_pk_fma_f32 v[162:163], v[176:177], v[24:25], v[162:163]
	v_pk_fma_f32 v[164:165], v[178:179], v[26:27], v[164:165]
	ds_read_b128 v[176:179], v196 offset:912
	s_waitcnt lgkmcnt(7)
	v_pk_fma_f32 v[28:29], v[180:181], v[192:193], v[28:29] op_sel_hi:[1,0,1] neg_lo:[0,1,0] neg_hi:[0,1,0]
	v_pk_fma_f32 v[30:31], v[182:183], v[192:193], v[30:31] op_sel_hi:[1,0,1] neg_lo:[0,1,0] neg_hi:[0,1,0]
	ds_read_b128 v[180:183], v196 offset:1168
	s_waitcnt lgkmcnt(7)
	v_pk_fma_f32 v[28:29], v[194:195], v[184:185], v[28:29] op_sel_hi:[0,1,1]
	v_pk_fma_f32 v[30:31], v[194:195], v[186:187], v[30:31] op_sel_hi:[0,1,1]
	ds_read_b128 v[184:187], v196 offset:672
	s_waitcnt lgkmcnt(7)
	v_pk_fma_f32 v[162:163], v[188:189], v[28:29], v[162:163]
	v_pk_fma_f32 v[164:165], v[190:191], v[30:31], v[164:165]
	ds_read_b128 v[188:191], v196 offset:928
	s_waitcnt lgkmcnt(7)
	v_pk_fma_f32 v[32:33], v[136:137], v[192:193], v[32:33] op_sel_hi:[1,0,1] neg_lo:[0,1,0] neg_hi:[0,1,0]
	v_pk_fma_f32 v[34:35], v[138:139], v[192:193], v[34:35] op_sel_hi:[1,0,1] neg_lo:[0,1,0] neg_hi:[0,1,0]
	ds_read_b128 v[136:139], v196 offset:1184
	s_waitcnt lgkmcnt(7)
	v_pk_fma_f32 v[32:33], v[194:195], v[140:141], v[32:33] op_sel_hi:[0,1,1]
	v_pk_fma_f32 v[34:35], v[194:195], v[142:143], v[34:35] op_sel_hi:[0,1,1]
	ds_read_b128 v[140:143], v196 offset:688
	s_waitcnt lgkmcnt(7)
	v_pk_fma_f32 v[162:163], v[144:145], v[32:33], v[162:163]
	v_pk_fma_f32 v[164:165], v[146:147], v[34:35], v[164:165]
	ds_read_b128 v[144:147], v196 offset:944
	s_waitcnt lgkmcnt(7)
	v_pk_fma_f32 v[36:37], v[148:149], v[192:193], v[36:37] op_sel_hi:[1,0,1] neg_lo:[0,1,0] neg_hi:[0,1,0]
	v_pk_fma_f32 v[38:39], v[150:151], v[192:193], v[38:39] op_sel_hi:[1,0,1] neg_lo:[0,1,0] neg_hi:[0,1,0]
	ds_read_b128 v[148:151], v196 offset:1200
	s_waitcnt lgkmcnt(7)
	v_pk_fma_f32 v[36:37], v[194:195], v[176:177], v[36:37] op_sel_hi:[0,1,1]
	v_pk_fma_f32 v[38:39], v[194:195], v[178:179], v[38:39] op_sel_hi:[0,1,1]
	ds_read_b128 v[176:179], v196 offset:704
	s_waitcnt lgkmcnt(7)
	v_pk_fma_f32 v[162:163], v[180:181], v[36:37], v[162:163]
	v_pk_fma_f32 v[164:165], v[182:183], v[38:39], v[164:165]
	ds_read_b128 v[180:183], v196 offset:960
	s_waitcnt lgkmcnt(7)
	v_pk_fma_f32 v[40:41], v[184:185], v[192:193], v[40:41] op_sel_hi:[1,0,1] neg_lo:[0,1,0] neg_hi:[0,1,0]
	v_pk_fma_f32 v[42:43], v[186:187], v[192:193], v[42:43] op_sel_hi:[1,0,1] neg_lo:[0,1,0] neg_hi:[0,1,0]
	ds_read_b128 v[184:187], v196 offset:1216
	s_waitcnt lgkmcnt(7)
	v_pk_fma_f32 v[40:41], v[194:195], v[188:189], v[40:41] op_sel_hi:[0,1,1]
	v_pk_fma_f32 v[42:43], v[194:195], v[190:191], v[42:43] op_sel_hi:[0,1,1]
	ds_read_b128 v[188:191], v196 offset:720
	s_waitcnt lgkmcnt(7)
	v_pk_fma_f32 v[162:163], v[136:137], v[40:41], v[162:163]
	v_pk_fma_f32 v[164:165], v[138:139], v[42:43], v[164:165]
	ds_read_b128 v[136:139], v196 offset:976
	s_waitcnt lgkmcnt(7)
	v_pk_fma_f32 v[44:45], v[140:141], v[192:193], v[44:45] op_sel_hi:[1,0,1] neg_lo:[0,1,0] neg_hi:[0,1,0]
	v_pk_fma_f32 v[46:47], v[142:143], v[192:193], v[46:47] op_sel_hi:[1,0,1] neg_lo:[0,1,0] neg_hi:[0,1,0]
	ds_read_b128 v[140:143], v196 offset:1232
	s_waitcnt lgkmcnt(7)
	v_pk_fma_f32 v[44:45], v[194:195], v[144:145], v[44:45] op_sel_hi:[0,1,1]
	v_pk_fma_f32 v[46:47], v[194:195], v[146:147], v[46:47] op_sel_hi:[0,1,1]
	ds_read_b128 v[144:147], v196 offset:736
	s_waitcnt lgkmcnt(7)
; template <int MODE> __device__ __forceinline__ void rwkv_item(const Params& P, int e, int c, int h, LAS float* slab, int lane) {
;     ...
;             f32x2 y0 = {0.f, 0.f}, y1 = {0.f, 0.f};
; #pragma unroll
;             for (int qb = 0; qb < NUB; ++qb) {
;                 if (NB == 2) { if (qb + 1 < NUB) RW_LD_UPD((qb + 1) & 1, qb + 1); } else RW_LD_UPD(0, qb);
;                 __builtin_amdgcn_sched_barrier(0);
; #pragma unroll
;                 for (int q = 0; q < UB; ++q) {
;                     const int qq = UB * qb + q;
;                     const f32x4 w4 = wq[qb & (NB - 1)][q], b4 = bq[qb & (NB - 1)][q], k4 = kq[qb & (NB - 1)][q];
;                     if (MODE == 0) {
;                         S2[2 * qq] = S2[2 * qq] * (f32x2){w4.x, w4.y} + (f32x2){b4.x, b4.y} * nsk;
;                         S2[2 * qq + 1] = S2[2 * qq + 1] * (f32x2){w4.z, w4.w} + (f32x2){b4.z, b4.w} * nsk;
;                         C2[2 * qq] = C2[2 * qq] * (f32x2){w4.x, w4.y} + (f32x2){b4.x, b4.y} * nskC + (f32x2){k4.x, k4.y} * v;
;                         C2[2 * qq + 1] = C2[2 * qq + 1] * (f32x2){w4.z, w4.w} + (f32x2){b4.z, b4.w} * nskC + (f32x2){k4.z, k4.w} * v;
;                     } else {
;                         S2[2 * qq] = S2[2 * qq] * (f32x2){w4.x, w4.y} + (f32x2){b4.x, b4.y} * nsk + (f32x2){k4.x, k4.y} * v;
;                         S2[2 * qq + 1] = S2[2 * qq + 1] * (f32x2){w4.z, w4.w} + (f32x2){b4.z, b4.w} * nsk + (f32x2){k4.z, k4.w} * v;
;                         const f32x4 r4 = rq[qb & (NB - 1)][q]; y0 += S2[2 * qq] * (f32x2){r4.x, r4.y}; y1 += S2[2 * qq + 1] * (f32x2){r4.z, r4.w};
;                     }
;                 }
;                 __builtin_amdgcn_sched_barrier(0);
;             }
;     ...
;             if (MODE == 1) ((LAS float*)st)[lane] = (y0.x + y0.y) + (y1.x + y1.y);
;         }
;         if (MODE == 1) {
;             LDS_WAIT();
; #pragma unroll
;             for (int s = 0; s < SB; ++s) {
;                 const LAS float* st = slab + s * 512;
;                 const float y = st[lane], v = st[320 + lane];
;                 const float mean = wave_sum(y) * (1.f / 64.f), d = y - mean;
;                 const float var = wave_sum(d * d) * (1.f / 64.f);
;                 const float yn = d * frsq(var + 64e-5f) * lnw + lnb;
;                 MIX[(size_t)(tb + s) * D + ch] = (bf16)f2bf((yn + st[384 + lane] * v) * st[448 + lane]);
;             }
;         }
	v_pk_fma_f32 v[162:163], v[148:149], v[44:45], v[162:163]
	v_pk_fma_f32 v[164:165], v[150:151], v[46:47], v[164:165]
	ds_read_b128 v[148:151], v196 offset:992
	s_waitcnt lgkmcnt(7)
	v_pk_fma_f32 v[48:49], v[176:177], v[192:193], v[48:49] op_sel_hi:[1,0,1] neg_lo:[0,1,0] neg_hi:[0,1,0]
	v_pk_fma_f32 v[50:51], v[178:179], v[192:193], v[50:51] op_sel_hi:[1,0,1] neg_lo:[0,1,0] neg_hi:[0,1,0]
	ds_read_b128 v[176:179], v196 offset:1248
	s_waitcnt lgkmcnt(7)
	v_pk_fma_f32 v[48:49], v[194:195], v[180:181], v[48:49] op_sel_hi:[0,1,1]
	v_pk_fma_f32 v[50:51], v[194:195], v[182:183], v[50:51] op_sel_hi:[0,1,1]
	ds_read_b128 v[180:183], v196 offset:752
	s_waitcnt lgkmcnt(7)
	v_pk_fma_f32 v[162:163], v[184:185], v[48:49], v[162:163]
	v_pk_fma_f32 v[164:165], v[186:187], v[50:51], v[164:165]
	ds_read_b128 v[184:187], v196 offset:1008
	s_waitcnt lgkmcnt(7)
	v_pk_fma_f32 v[52:53], v[188:189], v[192:193], v[52:53] op_sel_hi:[1,0,1] neg_lo:[0,1,0] neg_hi:[0,1,0]
	v_pk_fma_f32 v[54:55], v[190:191], v[192:193], v[54:55] op_sel_hi:[1,0,1] neg_lo:[0,1,0] neg_hi:[0,1,0]
	ds_read_b128 v[188:191], v196 offset:1264
	s_waitcnt lgkmcnt(7)
	v_pk_fma_f32 v[52:53], v[194:195], v[136:137], v[52:53] op_sel_hi:[0,1,1]
	v_pk_fma_f32 v[54:55], v[194:195], v[138:139], v[54:55] op_sel_hi:[0,1,1]
	s_waitcnt lgkmcnt(6)
	v_pk_fma_f32 v[162:163], v[140:141], v[52:53], v[162:163]
	v_pk_fma_f32 v[164:165], v[142:143], v[54:55], v[164:165]
	s_waitcnt lgkmcnt(5)
	v_pk_fma_f32 v[56:57], v[144:145], v[192:193], v[56:57] op_sel_hi:[1,0,1] neg_lo:[0,1,0] neg_hi:[0,1,0]
	v_pk_fma_f32 v[58:59], v[146:147], v[192:193], v[58:59] op_sel_hi:[1,0,1] neg_lo:[0,1,0] neg_hi:[0,1,0]
	s_waitcnt lgkmcnt(4)
	v_pk_fma_f32 v[56:57], v[194:195], v[148:149], v[56:57] op_sel_hi:[0,1,1]
	v_pk_fma_f32 v[58:59], v[194:195], v[150:151], v[58:59] op_sel_hi:[0,1,1]
	s_waitcnt lgkmcnt(3)
	v_pk_fma_f32 v[162:163], v[176:177], v[56:57], v[162:163]
	v_pk_fma_f32 v[164:165], v[178:179], v[58:59], v[164:165]
	s_waitcnt lgkmcnt(2)
	v_pk_fma_f32 v[60:61], v[180:181], v[192:193], v[60:61] op_sel_hi:[1,0,1] neg_lo:[0,1,0] neg_hi:[0,1,0]
	v_pk_fma_f32 v[62:63], v[182:183], v[192:193], v[62:63] op_sel_hi:[1,0,1] neg_lo:[0,1,0] neg_hi:[0,1,0]
	s_waitcnt lgkmcnt(1)
	v_pk_fma_f32 v[60:61], v[194:195], v[184:185], v[60:61] op_sel_hi:[0,1,1]
	v_pk_fma_f32 v[62:63], v[194:195], v[186:187], v[62:63] op_sel_hi:[0,1,1]
	s_waitcnt lgkmcnt(0)
	v_pk_fma_f32 v[162:163], v[188:189], v[60:61], v[162:163]
	v_pk_fma_f32 v[164:165], v[190:191], v[62:63], v[164:165]
	v_add_f32_e32 v198, v162, v163
	v_add_f32_e32 v192, v164, v165
	v_add_f32_e32 v198, v192, v198
	s_addk_i32 s11, 0x800
	ds_write_b32 v197, v198
	s_cmpk_eq_i32 s11, 0x4000
	s_cbranch_scc0 .Lm1_step
	s_waitcnt lgkmcnt(0)
	ds_read2st64_b32 v[200:201], v109 offset0:0 offset1:5
	ds_read2st64_b32 v[204:205], v109 offset0:6 offset1:7
	s_waitcnt lgkmcnt(1)
	v_add_f32_dpp v202, v200, v200 quad_perm:[1,0,3,2] row_mask:0xf bank_mask:0xf bound_ctrl:1
	s_nop 1
	v_add_f32_dpp v202, v202, v202 quad_perm:[2,3,0,1] row_mask:0xf bank_mask:0xf bound_ctrl:1
	s_nop 1
	v_add_f32_dpp v202, v202, v202 row_half_mirror row_mask:0xf bank_mask:0xf bound_ctrl:1
	s_nop 1
	v_add_f32_dpp v202, v202, v202 row_mirror row_mask:0xf bank_mask:0xf bound_ctrl:1
	s_nop 0
	v_readlane_b32 s8, v202, 16
	v_readlane_b32 s10, v202, 48
	v_readlane_b32 s0, v202, 0
	v_readlane_b32 s9, v202, 32
	v_mov_b32_e32 v202, s8
	v_mov_b32_e32 v203, s10
	v_add_f32_e32 v202, s0, v202
	v_add_f32_e32 v203, s9, v203
	v_add_f32_e32 v202, v202, v203
	v_fmamk_f32 v200, v202, 0xbc800000, v200
	v_mul_f32_e32 v202, v200, v200
	s_nop 1
	v_mov_b32_dpp v202, v202 quad_perm:[1,0,3,2] row_mask:0xf bank_mask:0xf bound_ctrl:1
	v_fmac_f32_e32 v202, v200, v200
	s_nop 1
	v_add_f32_dpp v202, v202, v202 quad_perm:[2,3,0,1] row_mask:0xf bank_mask:0xf bound_ctrl:1
	s_nop 1
	v_add_f32_dpp v202, v202, v202 row_half_mirror row_mask:0xf bank_mask:0xf bound_ctrl:1
	s_nop 1
	v_add_f32_dpp v202, v202, v202 row_mirror row_mask:0xf bank_mask:0xf bound_ctrl:1
	s_nop 0
	v_readlane_b32 s8, v202, 16
	v_readlane_b32 s10, v202, 48
	v_readlane_b32 s0, v202, 0
	v_readlane_b32 s9, v202, 32
	v_mov_b32_e32 v202, s8
	v_mov_b32_e32 v203, s10
	v_add_f32_e32 v202, s0, v202
	v_add_f32_e32 v203, s9, v203
	v_add_f32_e32 v202, v202, v203
	v_fmamk_f32 v202, v202, 0x3c800000, v221
	v_rsq_f32_e32 v202, v202
	v_add_u32_e32 v207, 0x0, v113
	v_mul_f32_e32 v200, v200, v202
	v_fma_f32 v200, v120, v200, v121
	s_waitcnt lgkmcnt(0)
	v_fmac_f32_e32 v200, v201, v204
	v_mul_f32_e32 v200, v205, v200
	v_bfe_u32 v203, v200, 16, 1
	v_add3_u32 v206, v200, v203, s33
	global_store_short_d16_hi v207, v206, s[70:71]
	ds_read2st64_b32 v[200:201], v109 offset0:8 offset1:13
	ds_read2st64_b32 v[204:205], v109 offset0:14 offset1:15
	s_waitcnt lgkmcnt(1)
	v_add_f32_dpp v202, v200, v200 quad_perm:[1,0,3,2] row_mask:0xf bank_mask:0xf bound_ctrl:1
	s_nop 1
	v_add_f32_dpp v202, v202, v202 quad_perm:[2,3,0,1] row_mask:0xf bank_mask:0xf bound_ctrl:1
	s_nop 1
	v_add_f32_dpp v202, v202, v202 row_half_mirror row_mask:0xf bank_mask:0xf bound_ctrl:1
	s_nop 1
	v_add_f32_dpp v202, v202, v202 row_mirror row_mask:0xf bank_mask:0xf bound_ctrl:1
	s_nop 0
	v_readlane_b32 s8, v202, 16
	v_readlane_b32 s10, v202, 48
	v_readlane_b32 s0, v202, 0
	v_readlane_b32 s9, v202, 32
	v_mov_b32_e32 v202, s8
	v_mov_b32_e32 v203, s10
	v_add_f32_e32 v202, s0, v202
	v_add_f32_e32 v203, s9, v203
	v_add_f32_e32 v202, v202, v203
	v_fmamk_f32 v200, v202, 0xbc800000, v200
	v_mul_f32_e32 v202, v200, v200
	s_nop 1
	v_mov_b32_dpp v202, v202 quad_perm:[1,0,3,2] row_mask:0xf bank_mask:0xf bound_ctrl:1
	v_fmac_f32_e32 v202, v200, v200
	s_nop 1
	v_add_f32_dpp v202, v202, v202 quad_perm:[2,3,0,1] row_mask:0xf bank_mask:0xf bound_ctrl:1
	s_nop 1
	v_add_f32_dpp v202, v202, v202 row_half_mirror row_mask:0xf bank_mask:0xf bound_ctrl:1
	s_nop 1
	v_add_f32_dpp v202, v202, v202 row_mirror row_mask:0xf bank_mask:0xf bound_ctrl:1
	s_nop 0
	v_readlane_b32 s8, v202, 16
	v_readlane_b32 s10, v202, 48
	v_readlane_b32 s0, v202, 0
	v_readlane_b32 s9, v202, 32
	v_mov_b32_e32 v202, s8
	v_mov_b32_e32 v203, s10
	v_add_f32_e32 v202, s0, v202
	v_add_f32_e32 v203, s9, v203
	v_add_f32_e32 v202, v202, v203
	v_fmamk_f32 v202, v202, 0x3c800000, v221
	v_rsq_f32_e32 v202, v202
	v_add_u32_e32 v207, 0x800, v113
	v_mul_f32_e32 v200, v200, v202
	v_fma_f32 v200, v120, v200, v121
	s_waitcnt lgkmcnt(0)
; #define LAS __attribute__((address_space(3)))
; __device__ __forceinline__ unsigned f2bf(float f) { unsigned u = __float_as_uint(f); return (u + 0x7fffu + ((u >> 16) & 1u)) >> 16; }
; __device__ __forceinline__ float frsq(float x) { return __builtin_amdgcn_rsqf(x); }
; #define LDS_WAIT() asm volatile("s_waitcnt lgkmcnt(0)" ::: "memory")
; template <int MODE> __device__ __forceinline__ void rwkv_item(const Params& P, int e, int c, int h, LAS float* slab, int lane) {
;     ...
;         if (MODE == 1) {
;             LDS_WAIT();
; #pragma unroll
;             for (int s = 0; s < SB; ++s) {
;                 const LAS float* st = slab + s * 512;
;                 const float y = st[lane], v = st[320 + lane];
;                 const float mean = wave_sum(y) * (1.f / 64.f), d = y - mean;
;                 const float var = wave_sum(d * d) * (1.f / 64.f);
;                 const float yn = d * frsq(var + 64e-5f) * lnw + lnb;
;                 MIX[(size_t)(tb + s) * D + ch] = (bf16)f2bf((yn + st[384 + lane] * v) * st[448 + lane]);
;             }
;         }
	v_fmac_f32_e32 v200, v201, v204
	v_mul_f32_e32 v200, v205, v200
	v_bfe_u32 v203, v200, 16, 1
	v_add3_u32 v206, v200, v203, s33
	global_store_short_d16_hi v207, v206, s[70:71]
	ds_read2st64_b32 v[200:201], v109 offset0:16 offset1:21
	ds_read2st64_b32 v[204:205], v109 offset0:22 offset1:23
	s_waitcnt lgkmcnt(1)
	v_add_f32_dpp v202, v200, v200 quad_perm:[1,0,3,2] row_mask:0xf bank_mask:0xf bound_ctrl:1
	s_nop 1
	v_add_f32_dpp v202, v202, v202 quad_perm:[2,3,0,1] row_mask:0xf bank_mask:0xf bound_ctrl:1
	s_nop 1
	v_add_f32_dpp v202, v202, v202 row_half_mirror row_mask:0xf bank_mask:0xf bound_ctrl:1
	s_nop 1
	v_add_f32_dpp v202, v202, v202 row_mirror row_mask:0xf bank_mask:0xf bound_ctrl:1
	s_nop 0
	v_readlane_b32 s8, v202, 16
	v_readlane_b32 s10, v202, 48
	v_readlane_b32 s0, v202, 0
	v_readlane_b32 s9, v202, 32
	v_mov_b32_e32 v202, s8
	v_mov_b32_e32 v203, s10
	v_add_f32_e32 v202, s0, v202
	v_add_f32_e32 v203, s9, v203
	v_add_f32_e32 v202, v202, v203
	v_fmamk_f32 v200, v202, 0xbc800000, v200
	v_mul_f32_e32 v202, v200, v200
	s_nop 1
	v_mov_b32_dpp v202, v202 quad_perm:[1,0,3,2] row_mask:0xf bank_mask:0xf bound_ctrl:1
	v_fmac_f32_e32 v202, v200, v200
	s_nop 1
	v_add_f32_dpp v202, v202, v202 quad_perm:[2,3,0,1] row_mask:0xf bank_mask:0xf bound_ctrl:1
	s_nop 1
	v_add_f32_dpp v202, v202, v202 row_half_mirror row_mask:0xf bank_mask:0xf bound_ctrl:1
	s_nop 1
	v_add_f32_dpp v202, v202, v202 row_mirror row_mask:0xf bank_mask:0xf bound_ctrl:1
	s_nop 0
	v_readlane_b32 s8, v202, 16
	v_readlane_b32 s10, v202, 48
	v_readlane_b32 s0, v202, 0
	v_readlane_b32 s9, v202, 32
	v_mov_b32_e32 v202, s8
	v_mov_b32_e32 v203, s10
	v_add_f32_e32 v202, s0, v202
	v_add_f32_e32 v203, s9, v203
	v_add_f32_e32 v202, v202, v203
	v_fmamk_f32 v202, v202, 0x3c800000, v221
	v_rsq_f32_e32 v202, v202
	v_add_u32_e32 v207, 0x1000, v113
	v_mul_f32_e32 v200, v200, v202
	v_fma_f32 v200, v120, v200, v121
	s_waitcnt lgkmcnt(0)
	v_fmac_f32_e32 v200, v201, v204
	v_mul_f32_e32 v200, v205, v200
	v_bfe_u32 v203, v200, 16, 1
	v_add3_u32 v206, v200, v203, s33
	global_store_short_d16_hi v207, v206, s[70:71]
	ds_read2st64_b32 v[200:201], v109 offset0:24 offset1:29
	ds_read2st64_b32 v[204:205], v109 offset0:30 offset1:31
	s_waitcnt lgkmcnt(1)
	v_add_f32_dpp v202, v200, v200 quad_perm:[1,0,3,2] row_mask:0xf bank_mask:0xf bound_ctrl:1
	s_nop 1
	v_add_f32_dpp v202, v202, v202 quad_perm:[2,3,0,1] row_mask:0xf bank_mask:0xf bound_ctrl:1
	s_nop 1
	v_add_f32_dpp v202, v202, v202 row_half_mirror row_mask:0xf bank_mask:0xf bound_ctrl:1
	s_nop 1
	v_add_f32_dpp v202, v202, v202 row_mirror row_mask:0xf bank_mask:0xf bound_ctrl:1
	s_nop 0
	v_readlane_b32 s8, v202, 16
	v_readlane_b32 s10, v202, 48
	v_readlane_b32 s0, v202, 0
	v_readlane_b32 s9, v202, 32
	v_mov_b32_e32 v202, s8
	v_mov_b32_e32 v203, s10
	v_add_f32_e32 v202, s0, v202
	v_add_f32_e32 v203, s9, v203
	v_add_f32_e32 v202, v202, v203
	v_fmamk_f32 v200, v202, 0xbc800000, v200
	v_mul_f32_e32 v202, v200, v200
	s_nop 1
	v_mov_b32_dpp v202, v202 quad_perm:[1,0,3,2] row_mask:0xf bank_mask:0xf bound_ctrl:1
	v_fmac_f32_e32 v202, v200, v200
	s_nop 1
	v_add_f32_dpp v202, v202, v202 quad_perm:[2,3,0,1] row_mask:0xf bank_mask:0xf bound_ctrl:1
	s_nop 1
	v_add_f32_dpp v202, v202, v202 row_half_mirror row_mask:0xf bank_mask:0xf bound_ctrl:1
	s_nop 1
	v_add_f32_dpp v202, v202, v202 row_mirror row_mask:0xf bank_mask:0xf bound_ctrl:1
	s_nop 0
	v_readlane_b32 s8, v202, 16
	v_readlane_b32 s10, v202, 48
	v_readlane_b32 s0, v202, 0
	v_readlane_b32 s9, v202, 32
	v_mov_b32_e32 v202, s8
	v_mov_b32_e32 v203, s10
	v_add_f32_e32 v202, s0, v202
	v_add_f32_e32 v203, s9, v203
	v_add_f32_e32 v202, v202, v203
	v_fmamk_f32 v202, v202, 0x3c800000, v221
	v_rsq_f32_e32 v202, v202
	v_add_u32_e32 v207, 0x1800, v113
	v_mul_f32_e32 v200, v200, v202
	v_fma_f32 v200, v120, v200, v121
	s_waitcnt lgkmcnt(0)
	v_fmac_f32_e32 v200, v201, v204
	v_mul_f32_e32 v200, v205, v200
	v_bfe_u32 v203, v200, 16, 1
	v_add3_u32 v206, v200, v203, s33
	global_store_short_d16_hi v207, v206, s[70:71]
	ds_read2st64_b32 v[200:201], v109 offset0:32 offset1:37
	ds_read2st64_b32 v[204:205], v109 offset0:38 offset1:39
	s_waitcnt lgkmcnt(1)
	v_add_f32_dpp v202, v200, v200 quad_perm:[1,0,3,2] row_mask:0xf bank_mask:0xf bound_ctrl:1
	s_nop 1
	v_add_f32_dpp v202, v202, v202 quad_perm:[2,3,0,1] row_mask:0xf bank_mask:0xf bound_ctrl:1
	s_nop 1
	v_add_f32_dpp v202, v202, v202 row_half_mirror row_mask:0xf bank_mask:0xf bound_ctrl:1
	s_nop 1
	v_add_f32_dpp v202, v202, v202 row_mirror row_mask:0xf bank_mask:0xf bound_ctrl:1
	s_nop 0
	v_readlane_b32 s8, v202, 16
	v_readlane_b32 s10, v202, 48
	v_readlane_b32 s0, v202, 0
	v_readlane_b32 s9, v202, 32
	v_mov_b32_e32 v202, s8
	v_mov_b32_e32 v203, s10
	v_add_f32_e32 v202, s0, v202
	v_add_f32_e32 v203, s9, v203
	v_add_f32_e32 v202, v202, v203
	v_fmamk_f32 v200, v202, 0xbc800000, v200
	v_mul_f32_e32 v202, v200, v200
	s_nop 1
	v_mov_b32_dpp v202, v202 quad_perm:[1,0,3,2] row_mask:0xf bank_mask:0xf bound_ctrl:1
	v_fmac_f32_e32 v202, v200, v200
	s_nop 1
	v_add_f32_dpp v202, v202, v202 quad_perm:[2,3,0,1] row_mask:0xf bank_mask:0xf bound_ctrl:1
	s_nop 1
	v_add_f32_dpp v202, v202, v202 row_half_mirror row_mask:0xf bank_mask:0xf bound_ctrl:1
	s_nop 1
	v_add_f32_dpp v202, v202, v202 row_mirror row_mask:0xf bank_mask:0xf bound_ctrl:1
	s_nop 0
	v_readlane_b32 s8, v202, 16
	v_readlane_b32 s10, v202, 48
	v_readlane_b32 s0, v202, 0
	v_readlane_b32 s9, v202, 32
	v_mov_b32_e32 v202, s8
	v_mov_b32_e32 v203, s10
	v_add_f32_e32 v202, s0, v202
	v_add_f32_e32 v203, s9, v203
	v_add_f32_e32 v202, v202, v203
	v_fmamk_f32 v202, v202, 0x3c800000, v221
	v_rsq_f32_e32 v202, v202
	v_add_u32_e32 v207, 0x2000, v113
	v_mul_f32_e32 v200, v200, v202
	v_fma_f32 v200, v120, v200, v121
	s_waitcnt lgkmcnt(0)
; #define LAS __attribute__((address_space(3)))
; __device__ __forceinline__ unsigned f2bf(float f) { unsigned u = __float_as_uint(f); return (u + 0x7fffu + ((u >> 16) & 1u)) >> 16; }
; __device__ __forceinline__ float frsq(float x) { return __builtin_amdgcn_rsqf(x); }
; #define LDS_WAIT() asm volatile("s_waitcnt lgkmcnt(0)" ::: "memory")
; template <int MODE> __device__ __forceinline__ void rwkv_item(const Params& P, int e, int c, int h, LAS float* slab, int lane) {
;     ...
;         if (MODE == 1) {
;             LDS_WAIT();
; #pragma unroll
;             for (int s = 0; s < SB; ++s) {
;                 const LAS float* st = slab + s * 512;
;                 const float y = st[lane], v = st[320 + lane];
;                 const float mean = wave_sum(y) * (1.f / 64.f), d = y - mean;
;                 const float var = wave_sum(d * d) * (1.f / 64.f);
;                 const float yn = d * frsq(var + 64e-5f) * lnw + lnb;
;                 MIX[(size_t)(tb + s) * D + ch] = (bf16)f2bf((yn + st[384 + lane] * v) * st[448 + lane]);
;             }
;         }
;         LDS_WAIT();
;     }
	v_fmac_f32_e32 v200, v201, v204
	v_mul_f32_e32 v200, v205, v200
	v_bfe_u32 v203, v200, 16, 1
	v_add3_u32 v206, v200, v203, s33
	global_store_short_d16_hi v207, v206, s[70:71]
	ds_read2st64_b32 v[200:201], v109 offset0:40 offset1:45
	ds_read2st64_b32 v[204:205], v109 offset0:46 offset1:47
	s_waitcnt lgkmcnt(1)
	v_add_f32_dpp v202, v200, v200 quad_perm:[1,0,3,2] row_mask:0xf bank_mask:0xf bound_ctrl:1
	s_nop 1
	v_add_f32_dpp v202, v202, v202 quad_perm:[2,3,0,1] row_mask:0xf bank_mask:0xf bound_ctrl:1
	s_nop 1
	v_add_f32_dpp v202, v202, v202 row_half_mirror row_mask:0xf bank_mask:0xf bound_ctrl:1
	s_nop 1
	v_add_f32_dpp v202, v202, v202 row_mirror row_mask:0xf bank_mask:0xf bound_ctrl:1
	s_nop 0
	v_readlane_b32 s8, v202, 16
	v_readlane_b32 s10, v202, 48
	v_readlane_b32 s0, v202, 0
	v_readlane_b32 s9, v202, 32
	v_mov_b32_e32 v202, s8
	v_mov_b32_e32 v203, s10
	v_add_f32_e32 v202, s0, v202
	v_add_f32_e32 v203, s9, v203
	v_add_f32_e32 v202, v202, v203
	v_fmamk_f32 v200, v202, 0xbc800000, v200
	v_mul_f32_e32 v202, v200, v200
	s_nop 1
	v_mov_b32_dpp v202, v202 quad_perm:[1,0,3,2] row_mask:0xf bank_mask:0xf bound_ctrl:1
	v_fmac_f32_e32 v202, v200, v200
	s_nop 1
	v_add_f32_dpp v202, v202, v202 quad_perm:[2,3,0,1] row_mask:0xf bank_mask:0xf bound_ctrl:1
	s_nop 1
	v_add_f32_dpp v202, v202, v202 row_half_mirror row_mask:0xf bank_mask:0xf bound_ctrl:1
	s_nop 1
	v_add_f32_dpp v202, v202, v202 row_mirror row_mask:0xf bank_mask:0xf bound_ctrl:1
	s_nop 0
	v_readlane_b32 s8, v202, 16
	v_readlane_b32 s10, v202, 48
	v_readlane_b32 s0, v202, 0
	v_readlane_b32 s9, v202, 32
	v_mov_b32_e32 v202, s8
	v_mov_b32_e32 v203, s10
	v_add_f32_e32 v202, s0, v202
	v_add_f32_e32 v203, s9, v203
	v_add_f32_e32 v202, v202, v203
	v_fmamk_f32 v202, v202, 0x3c800000, v221
	v_rsq_f32_e32 v202, v202
	v_add_u32_e32 v207, 0x2800, v113
	v_mul_f32_e32 v200, v200, v202
	v_fma_f32 v200, v120, v200, v121
	s_waitcnt lgkmcnt(0)
	v_fmac_f32_e32 v200, v201, v204
	v_mul_f32_e32 v200, v205, v200
	v_bfe_u32 v203, v200, 16, 1
	v_add3_u32 v206, v200, v203, s33
	global_store_short_d16_hi v207, v206, s[70:71]
	ds_read2st64_b32 v[200:201], v109 offset0:48 offset1:53
	ds_read2st64_b32 v[204:205], v109 offset0:54 offset1:55
	s_waitcnt lgkmcnt(1)
	v_add_f32_dpp v202, v200, v200 quad_perm:[1,0,3,2] row_mask:0xf bank_mask:0xf bound_ctrl:1
	s_nop 1
	v_add_f32_dpp v202, v202, v202 quad_perm:[2,3,0,1] row_mask:0xf bank_mask:0xf bound_ctrl:1
	s_nop 1
	v_add_f32_dpp v202, v202, v202 row_half_mirror row_mask:0xf bank_mask:0xf bound_ctrl:1
	s_nop 1
	v_add_f32_dpp v202, v202, v202 row_mirror row_mask:0xf bank_mask:0xf bound_ctrl:1
	s_nop 0
	v_readlane_b32 s8, v202, 16
	v_readlane_b32 s10, v202, 48
	v_readlane_b32 s0, v202, 0
	v_readlane_b32 s9, v202, 32
	v_mov_b32_e32 v202, s8
	v_mov_b32_e32 v203, s10
	v_add_f32_e32 v202, s0, v202
	v_add_f32_e32 v203, s9, v203
	v_add_f32_e32 v202, v202, v203
	v_fmamk_f32 v200, v202, 0xbc800000, v200
	v_mul_f32_e32 v202, v200, v200
	s_nop 1
	v_mov_b32_dpp v202, v202 quad_perm:[1,0,3,2] row_mask:0xf bank_mask:0xf bound_ctrl:1
	v_fmac_f32_e32 v202, v200, v200
	s_nop 1
	v_add_f32_dpp v202, v202, v202 quad_perm:[2,3,0,1] row_mask:0xf bank_mask:0xf bound_ctrl:1
	s_nop 1
	v_add_f32_dpp v202, v202, v202 row_half_mirror row_mask:0xf bank_mask:0xf bound_ctrl:1
	s_nop 1
	v_add_f32_dpp v202, v202, v202 row_mirror row_mask:0xf bank_mask:0xf bound_ctrl:1
	s_nop 0
	v_readlane_b32 s8, v202, 16
	v_readlane_b32 s10, v202, 48
	v_readlane_b32 s0, v202, 0
	v_readlane_b32 s9, v202, 32
	v_mov_b32_e32 v202, s8
	v_mov_b32_e32 v203, s10
	v_add_f32_e32 v202, s0, v202
	v_add_f32_e32 v203, s9, v203
	v_add_f32_e32 v202, v202, v203
	v_fmamk_f32 v202, v202, 0x3c800000, v221
	v_rsq_f32_e32 v202, v202
	v_add_u32_e32 v207, 0x3000, v113
	v_mul_f32_e32 v200, v200, v202
	v_fma_f32 v200, v120, v200, v121
	s_waitcnt lgkmcnt(0)
	v_fmac_f32_e32 v200, v201, v204
	v_mul_f32_e32 v200, v205, v200
	v_bfe_u32 v203, v200, 16, 1
	v_add3_u32 v206, v200, v203, s33
	global_store_short_d16_hi v207, v206, s[70:71]
	ds_read2st64_b32 v[200:201], v109 offset0:56 offset1:61
	ds_read2st64_b32 v[204:205], v109 offset0:62 offset1:63
	s_waitcnt lgkmcnt(1)
	v_add_f32_dpp v202, v200, v200 quad_perm:[1,0,3,2] row_mask:0xf bank_mask:0xf bound_ctrl:1
	s_nop 1
	v_add_f32_dpp v202, v202, v202 quad_perm:[2,3,0,1] row_mask:0xf bank_mask:0xf bound_ctrl:1
	s_nop 1
	v_add_f32_dpp v202, v202, v202 row_half_mirror row_mask:0xf bank_mask:0xf bound_ctrl:1
	s_nop 1
	v_add_f32_dpp v202, v202, v202 row_mirror row_mask:0xf bank_mask:0xf bound_ctrl:1
	s_nop 0
	v_readlane_b32 s8, v202, 16
	v_readlane_b32 s10, v202, 48
	v_readlane_b32 s0, v202, 0
	v_readlane_b32 s9, v202, 32
	v_mov_b32_e32 v202, s8
	v_mov_b32_e32 v203, s10
	v_add_f32_e32 v202, s0, v202
	v_add_f32_e32 v203, s9, v203
	v_add_f32_e32 v202, v202, v203
	v_fmamk_f32 v200, v202, 0xbc800000, v200
	v_mul_f32_e32 v202, v200, v200
	s_nop 1
	v_mov_b32_dpp v202, v202 quad_perm:[1,0,3,2] row_mask:0xf bank_mask:0xf bound_ctrl:1
	v_fmac_f32_e32 v202, v200, v200
	s_nop 1
	v_add_f32_dpp v202, v202, v202 quad_perm:[2,3,0,1] row_mask:0xf bank_mask:0xf bound_ctrl:1
	s_nop 1
	v_add_f32_dpp v202, v202, v202 row_half_mirror row_mask:0xf bank_mask:0xf bound_ctrl:1
	s_nop 1
	v_add_f32_dpp v202, v202, v202 row_mirror row_mask:0xf bank_mask:0xf bound_ctrl:1
	s_nop 0
	v_readlane_b32 s8, v202, 16
	v_readlane_b32 s10, v202, 48
	v_readlane_b32 s0, v202, 0
	v_readlane_b32 s9, v202, 32
	v_mov_b32_e32 v202, s8
	v_mov_b32_e32 v203, s10
	v_add_f32_e32 v202, s0, v202
	v_add_f32_e32 v203, s9, v203
	v_add_f32_e32 v202, v202, v203
	v_fmamk_f32 v202, v202, 0x3c800000, v221
	v_rsq_f32_e32 v202, v202
	v_add_u32_e32 v207, 0x3800, v113
	v_mul_f32_e32 v200, v200, v202
	v_fma_f32 v200, v120, v200, v121
	s_waitcnt lgkmcnt(0)
	v_fmac_f32_e32 v200, v201, v204
	v_mul_f32_e32 v200, v205, v200
	v_bfe_u32 v203, v200, 16, 1
	v_add3_u32 v206, v200, v203, s33
	global_store_short_d16_hi v207, v206, s[70:71]
	v_add_u32_e32 v113, 0x4000, v113
	s_add_i32 s1, s1, 1
	s_cmp_eq_u32 s1, 8
	s_cbranch_scc0 .Lm1_sub
	s_add_i32 s2, s2, s58
	s_cmpk_gt_i32 s2, 0x7ff
	s_cbranch_scc0 .LBB0_205
	s_load_dwordx2 s[72:73], s[30:31], 0x118
	v_readlane_b32 s12, v253, 17
	v_readlane_b32 s13, v253, 18
	v_readlane_b32 s67, v255, 14
	v_readlane_b32 s71, v255, 15
	v_readlane_b32 s51, v255, 16

; template <int MODE> __device__ __forceinline__ void rwkv_item(const Params& P, int e, int c, int h, LAS float* slab, int lane) {
;     ...
;     const int ch = h * 64 + lane;
;     const float mu_r = P.in[I_AMU][(size_t)e * DINA + ch], mu_k = P.in[I_AMU][(size_t)e * DINA + 512 + ch];
;     const float kkw = P.in[I_AKK][e * 512 + ch], ka = P.in[I_AKA][e * 512 + ch], rk = P.in[I_ARK][e * 512 + ch];
;     const float lnw = P.in[I_ALNW][e * 512 + ch], lnb = P.in[I_ALNB][e * 512 + ch];
;     constexpr int SB = MODE == 0 ? 4 : 8;
;     f32x2 S2[32], C2[MODE == 0 ? 32 : 1];
;     const size_t rowoff = (((size_t)c * 8 + h) * 64 + lane) * 64;
;     if (MODE == 0) {
; #pragma unroll
;         for (int i = 0; i < 32; ++i) { S2[i] = (f32x2){(2 * i) == lane ? 1.f : 0.f, (2 * i + 1) == lane ? 1.f : 0.f}; C2[i] = (f32x2){0.f, 0.f}; }
;     } else {
; #pragma unroll
;         for (int q = 0; q < 16; ++q) { const f32x4 v = *(const f32x4*)(MCC + rowoff + 4 * q); S2[2 * q] = (f32x2){v.x, v.y}; S2[2 * q + 1] = (f32x2){v.z, v.w}; }
;     }
;     float r1[SB + 1], k1[SB + 1], vv[SB], dd[SB], aa[SB], gg[MODE == 1 ? SB : 1];
.LBB0_262:
	s_and_b32 s22, s20, 7
	s_lshl_b32 s22, s22, 6
	s_ashr_i32 s0, s20, 3
	s_lshl_b32 s1, s0, 6
	v_readlane_b32 s2, v255, 8
	v_or_b32_e32 v210, s22, v128
	v_lshlrev_b32_e32 v207, 2, v210
	global_load_dword v230, v207, s[12:13] offset:2048
	v_or_b32_e32 v204, s2, v210
	v_lshlrev_b32_e32 v204, 2, v204
	global_load_dword v231, v204, s[4:5]
	global_load_dword v232, v204, s[6:7]
	s_mul_i32 s2, s1, 0xe00
	s_add_i32 s2, s2, 0x400
	v_lshl_add_u32 v201, v210, 1, s2
	s_lshl_b32 s2, s1, 10
	v_lshl_add_u32 v202, v210, 1, s2
	s_lshl_b32 s2, s1, 11
	v_lshl_add_u32 v203, v210, 2, s2
	s_cmp_eq_u32 s0, 0
	s_cselect_b32 s2, 0, 0xe00
	v_subrev_u32_e32 v204, s2, v201
	global_load_ushort v200, v204, s[26:27]
	global_load_ushort v168, v201, s[26:27]
	global_load_ushort v169, v201, s[26:27] offset:3584
	v_add_u32_e32 v204, 0x1c00, v201
	v_add_u32_e32 v205, 0x3800, v201
	v_add_u32_e32 v206, 0x5400, v201
	global_load_ushort v170, v204, s[26:27]
	global_load_ushort v171, v204, s[26:27] offset:3584
	global_load_ushort v172, v205, s[26:27]
	global_load_ushort v173, v205, s[26:27] offset:3584
	global_load_ushort v174, v206, s[26:27]
	global_load_ushort v175, v206, s[26:27] offset:3584
	v_add_u32_e32 v204, 0x1000, v202
	global_load_ushort v176, v202, s[14:15]
	global_load_ushort v177, v202, s[14:15] offset:1024
	global_load_ushort v178, v202, s[14:15] offset:2048
	global_load_ushort v179, v202, s[14:15] offset:3072
	global_load_ushort v180, v204, s[14:15]
	global_load_ushort v181, v204, s[14:15] offset:1024
	global_load_ushort v182, v204, s[14:15] offset:2048
	global_load_ushort v183, v204, s[14:15] offset:3072
	global_load_ushort v192, v202, s[16:17]
	global_load_ushort v193, v202, s[16:17] offset:1024
	global_load_ushort v194, v202, s[16:17] offset:2048
	global_load_ushort v195, v202, s[16:17] offset:3072
	global_load_ushort v196, v204, s[16:17]
	global_load_ushort v197, v204, s[16:17] offset:1024
	global_load_ushort v198, v204, s[16:17] offset:2048
	global_load_ushort v199, v204, s[16:17] offset:3072
	v_add_u32_e32 v205, 0x1000, v203
	v_add_u32_e32 v206, 0x2000, v203
	v_add_u32_e32 v207, 0x3000, v203
	global_load_dword v184, v203, s[10:11]
	global_load_dword v185, v203, s[10:11] offset:2048
	global_load_dword v186, v205, s[10:11]
	global_load_dword v187, v205, s[10:11] offset:2048
	global_load_dword v188, v206, s[10:11]
	global_load_dword v189, v206, s[10:11] offset:2048
	global_load_dword v190, v207, s[10:11]
	global_load_dword v191, v207, s[10:11] offset:2048
	v_add_u32_e32 v201, 0x7000, v201
	v_add_u32_e32 v202, 0x2000, v202
	v_add_u32_e32 v203, 0x4000, v203
	v_cmp_eq_u32_e32 vcc, 0, v128
	v_mov_b32_e32 v124, 0
	s_nop 0
	v_cndmask_b32_e64 v112, 0, 1.0, vcc
	v_cmp_eq_u32_e32 vcc, 1, v128
	v_mov_b32_e32 v125, 0
	s_nop 0
	v_cndmask_b32_e64 v113, 0, 1.0, vcc
	v_cmp_eq_u32_e32 vcc, 2, v128
	v_mov_b32_e32 v126, 0
	s_nop 0
	v_cndmask_b32_e64 v114, 0, 1.0, vcc
	v_cmp_eq_u32_e32 vcc, 3, v128
	v_mov_b32_e32 v127, 0
	s_nop 0
	v_cndmask_b32_e64 v115, 0, 1.0, vcc
	v_cmp_eq_u32_e32 vcc, 4, v128
	v_mov_b32_e32 v120, 0
	s_nop 0
	v_cndmask_b32_e64 v104, 0, 1.0, vcc
	v_cmp_eq_u32_e32 vcc, 5, v128
	v_mov_b32_e32 v121, 0
	s_nop 0
	v_cndmask_b32_e64 v105, 0, 1.0, vcc
	v_cmp_eq_u32_e32 vcc, 6, v128
	v_mov_b32_e32 v122, 0
	s_nop 0
	v_cndmask_b32_e64 v106, 0, 1.0, vcc
	v_cmp_eq_u32_e32 vcc, 7, v128
	v_mov_b32_e32 v123, 0
	s_nop 0
	v_cndmask_b32_e64 v107, 0, 1.0, vcc
	v_cmp_eq_u32_e32 vcc, 8, v128
	v_mov_b32_e32 v116, 0
	s_nop 0
	v_cndmask_b32_e64 v92, 0, 1.0, vcc
	v_cmp_eq_u32_e32 vcc, 9, v128
	v_mov_b32_e32 v117, 0
	s_nop 0
	v_cndmask_b32_e64 v93, 0, 1.0, vcc
	v_cmp_eq_u32_e32 vcc, 10, v128
	v_mov_b32_e32 v118, 0
	s_nop 0
	v_cndmask_b32_e64 v94, 0, 1.0, vcc
	v_cmp_eq_u32_e32 vcc, 11, v128
	v_mov_b32_e32 v119, 0
	s_nop 0
	v_cndmask_b32_e64 v95, 0, 1.0, vcc
	v_cmp_eq_u32_e32 vcc, 12, v128
	v_mov_b32_e32 v108, 0
	s_nop 0
	v_cndmask_b32_e64 v76, 0, 1.0, vcc
	v_cmp_eq_u32_e32 vcc, 13, v128
	v_mov_b32_e32 v109, 0
	s_nop 0
	v_cndmask_b32_e64 v77, 0, 1.0, vcc
	v_cmp_eq_u32_e32 vcc, 14, v128
	v_mov_b32_e32 v110, 0
	s_nop 0
	v_cndmask_b32_e64 v78, 0, 1.0, vcc
	v_cmp_eq_u32_e32 vcc, 15, v128
	v_mov_b32_e32 v111, 0
	s_nop 0
	v_cndmask_b32_e64 v79, 0, 1.0, vcc
	v_cmp_eq_u32_e32 vcc, 16, v128
	v_mov_b32_e32 v96, 0
	s_nop 0
	v_cndmask_b32_e64 v64, 0, 1.0, vcc
	v_cmp_eq_u32_e32 vcc, 17, v128
	v_mov_b32_e32 v97, 0
	s_nop 0
	v_cndmask_b32_e64 v65, 0, 1.0, vcc
	v_cmp_eq_u32_e32 vcc, 18, v128
	v_mov_b32_e32 v98, 0
	s_nop 0
	v_cndmask_b32_e64 v66, 0, 1.0, vcc
	v_cmp_eq_u32_e32 vcc, 19, v128
	v_mov_b32_e32 v99, 0
	s_nop 0
	v_cndmask_b32_e64 v67, 0, 1.0, vcc
	v_cmp_eq_u32_e32 vcc, 20, v128
	v_mov_b32_e32 v80, 0
	s_nop 0
	v_cndmask_b32_e64 v100, 0, 1.0, vcc
	v_cmp_eq_u32_e32 vcc, 21, v128
	v_mov_b32_e32 v81, 0
	s_nop 0
	v_cndmask_b32_e64 v101, 0, 1.0, vcc
	v_cmp_eq_u32_e32 vcc, 22, v128
	v_mov_b32_e32 v82, 0
	s_nop 0
	v_cndmask_b32_e64 v102, 0, 1.0, vcc
	v_cmp_eq_u32_e32 vcc, 23, v128
	v_mov_b32_e32 v83, 0
	s_nop 0
	v_cndmask_b32_e64 v103, 0, 1.0, vcc
	v_cmp_eq_u32_e32 vcc, 24, v128
	v_mov_b32_e32 v68, 0
	s_nop 0
	v_cndmask_b32_e64 v88, 0, 1.0, vcc
	v_cmp_eq_u32_e32 vcc, 25, v128
	v_mov_b32_e32 v69, 0
	s_nop 0
	v_cndmask_b32_e64 v89, 0, 1.0, vcc
	v_cmp_eq_u32_e32 vcc, 26, v128
	v_mov_b32_e32 v70, 0
	s_nop 0
	v_cndmask_b32_e64 v90, 0, 1.0, vcc
	v_cmp_eq_u32_e32 vcc, 27, v128
	v_mov_b32_e32 v71, 0
	s_nop 0
	v_cndmask_b32_e64 v91, 0, 1.0, vcc
	v_cmp_eq_u32_e32 vcc, 28, v128
	v_mov_b32_e32 v52, 0
	s_nop 0
	v_cndmask_b32_e64 v84, 0, 1.0, vcc
	v_cmp_eq_u32_e32 vcc, 29, v128
	v_mov_b32_e32 v53, 0
	s_nop 0
	v_cndmask_b32_e64 v85, 0, 1.0, vcc
	v_cmp_eq_u32_e32 vcc, 30, v128
	v_mov_b32_e32 v54, 0
	s_nop 0
; #define LAS __attribute__((address_space(3)))
; __device__ __forceinline__ float frsq(float x) { return __builtin_amdgcn_rsqf(x); }
; template <int MODE> __device__ __forceinline__ void rwkv_item(const Params& P, int e, int c, int h, LAS float* slab, int lane) {
;     ...
;         for (int i = 0; i < 32; ++i) { S2[i] = (f32x2){(2 * i) == lane ? 1.f : 0.f, (2 * i + 1) == lane ? 1.f : 0.f}; C2[i] = (f32x2){0.f, 0.f}; }
;     ...
; #pragma unroll
;         for (int s = 0; s < SB; ++s) {
;             const float r = r1[s + 1] + (r1[s] - r1[s + 1]) * mu_r, k = k1[s + 1] + (k1[s] - k1[s + 1]) * mu_k, a = aa[s];
;             float kk = k * kkw;
;             const float ss = wave_sum(kk * kk);
;             kk *= frsq(fmaxf(ss, 1e-24f));
;             const float b = kk * a, kp = k * (1.f + (a - 1.f) * ka);
;             LAS float* st = slab + s * 512;
;             st[lane] = dd[s]; st[64 + lane] = kk; st[128 + lane] = b; st[192 + lane] = kp; st[256 + lane] = r; st[320 + lane] = vv[s];
	v_cndmask_b32_e64 v86, 0, 1.0, vcc
	v_cmp_eq_u32_e32 vcc, 31, v128
	v_mov_b32_e32 v55, 0
	s_nop 0
	v_cndmask_b32_e64 v87, 0, 1.0, vcc
	v_cmp_eq_u32_e32 vcc, 32, v128
	v_mov_b32_e32 v44, 0
	s_nop 0
	v_cndmask_b32_e64 v72, 0, 1.0, vcc
	v_cmp_eq_u32_e32 vcc, 33, v128
	v_mov_b32_e32 v45, 0
	s_nop 0
	v_cndmask_b32_e64 v73, 0, 1.0, vcc
	v_cmp_eq_u32_e32 vcc, 34, v128
	v_mov_b32_e32 v46, 0
	s_nop 0
	v_cndmask_b32_e64 v74, 0, 1.0, vcc
	v_cmp_eq_u32_e32 vcc, 35, v128
	v_mov_b32_e32 v47, 0
	s_nop 0
	v_cndmask_b32_e64 v75, 0, 1.0, vcc
	v_cmp_eq_u32_e32 vcc, 36, v128
	v_mov_b32_e32 v32, 0
	s_nop 0
	v_cndmask_b32_e64 v60, 0, 1.0, vcc
	v_cmp_eq_u32_e32 vcc, 37, v128
	v_mov_b32_e32 v33, 0
	s_nop 0
	v_cndmask_b32_e64 v61, 0, 1.0, vcc
	v_cmp_eq_u32_e32 vcc, 38, v128
	v_mov_b32_e32 v34, 0
	s_nop 0
	v_cndmask_b32_e64 v62, 0, 1.0, vcc
	v_cmp_eq_u32_e32 vcc, 39, v128
	v_mov_b32_e32 v35, 0
	s_nop 0
	v_cndmask_b32_e64 v63, 0, 1.0, vcc
	v_cmp_eq_u32_e32 vcc, 40, v128
	v_mov_b32_e32 v24, 0
	s_nop 0
	v_cndmask_b32_e64 v56, 0, 1.0, vcc
	v_cmp_eq_u32_e32 vcc, 41, v128
	v_mov_b32_e32 v25, 0
	s_nop 0
	v_cndmask_b32_e64 v57, 0, 1.0, vcc
	v_cmp_eq_u32_e32 vcc, 42, v128
	v_mov_b32_e32 v26, 0
	s_nop 0
	v_cndmask_b32_e64 v58, 0, 1.0, vcc
	v_cmp_eq_u32_e32 vcc, 43, v128
	v_mov_b32_e32 v27, 0
	s_nop 0
	v_cndmask_b32_e64 v59, 0, 1.0, vcc
	v_cmp_eq_u32_e32 vcc, 44, v128
	v_mov_b32_e32 v16, 0
	s_nop 0
	v_cndmask_b32_e64 v48, 0, 1.0, vcc
	v_cmp_eq_u32_e32 vcc, 45, v128
	v_mov_b32_e32 v17, 0
	s_nop 0
	v_cndmask_b32_e64 v49, 0, 1.0, vcc
	v_cmp_eq_u32_e32 vcc, 46, v128
	v_mov_b32_e32 v18, 0
	s_nop 0
	v_cndmask_b32_e64 v50, 0, 1.0, vcc
	v_cmp_eq_u32_e32 vcc, 47, v128
	v_mov_b32_e32 v19, 0
	s_nop 0
	v_cndmask_b32_e64 v51, 0, 1.0, vcc
	v_cmp_eq_u32_e32 vcc, 48, v128
	v_mov_b32_e32 v12, 0
	s_nop 0
	v_cndmask_b32_e64 v40, 0, 1.0, vcc
	v_cmp_eq_u32_e32 vcc, 49, v128
	v_mov_b32_e32 v13, 0
	s_nop 0
	v_cndmask_b32_e64 v41, 0, 1.0, vcc
	v_cmp_eq_u32_e32 vcc, 50, v128
	v_mov_b32_e32 v14, 0
	s_nop 0
	v_cndmask_b32_e64 v42, 0, 1.0, vcc
	v_cmp_eq_u32_e32 vcc, 51, v128
	v_mov_b32_e32 v15, 0
	s_nop 0
	v_cndmask_b32_e64 v43, 0, 1.0, vcc
	v_cmp_eq_u32_e32 vcc, 52, v128
	v_mov_b32_e32 v8, 0
	s_nop 0
	v_cndmask_b32_e64 v36, 0, 1.0, vcc
	v_cmp_eq_u32_e32 vcc, 53, v128
	v_mov_b32_e32 v9, 0
	s_nop 0
	v_cndmask_b32_e64 v37, 0, 1.0, vcc
	v_cmp_eq_u32_e32 vcc, 54, v128
	v_mov_b32_e32 v10, 0
	s_nop 0
	v_cndmask_b32_e64 v38, 0, 1.0, vcc
	v_cmp_eq_u32_e32 vcc, 55, v128
	v_mov_b32_e32 v11, 0
	s_nop 0
	v_cndmask_b32_e64 v39, 0, 1.0, vcc
	v_cmp_eq_u32_e32 vcc, 56, v128
	v_mov_b32_e32 v4, 0
	s_nop 0
	v_cndmask_b32_e64 v28, 0, 1.0, vcc
	v_cmp_eq_u32_e32 vcc, 57, v128
	v_mov_b32_e32 v5, 0
	s_nop 0
	v_cndmask_b32_e64 v29, 0, 1.0, vcc
	v_cmp_eq_u32_e32 vcc, 58, v128
	v_mov_b32_e32 v6, 0
	s_nop 0
	v_cndmask_b32_e64 v30, 0, 1.0, vcc
	v_cmp_eq_u32_e32 vcc, 59, v128
	v_mov_b32_e32 v7, 0
	s_nop 0
	v_cndmask_b32_e64 v31, 0, 1.0, vcc
	v_cmp_eq_u32_e32 vcc, 60, v128
	v_mov_b32_e32 v0, 0
	s_nop 0
	v_cndmask_b32_e64 v20, 0, 1.0, vcc
	v_cmp_eq_u32_e32 vcc, 61, v128
	v_mov_b32_e32 v1, 0
	s_nop 0
	v_cndmask_b32_e64 v21, 0, 1.0, vcc
	v_cmp_eq_u32_e32 vcc, 62, v128
	v_mov_b32_e32 v2, 0
	s_nop 0
	v_cndmask_b32_e64 v22, 0, 1.0, vcc
	v_cmp_eq_u32_e32 vcc, 63, v128
	v_mov_b32_e32 v3, 0
	s_nop 0
	v_cndmask_b32_e64 v23, 0, 1.0, vcc
	s_mov_b32 s23, 0
	v_mov_b32_e32 v137, 1.0
	s_cmp_gt_i32 s0, 0
	s_cselect_b64 vcc, -1, 0
	s_waitcnt vmcnt(32)
	v_lshlrev_b32_e32 v200, 16, v200
	v_cndmask_b32_e32 v200, 0, v200, vcc
.Lm0_sub:
	s_waitcnt vmcnt(0)
	v_lshlrev_b32_e32 v136, 16, v168
	v_sub_f32_e32 v130, v200, v136
	v_fma_f32 v130, v230, v130, v136
	v_mul_f32_e32 v131, v231, v130
	v_mul_f32_e32 v132, v131, v131
	v_lshlrev_b32_e32 v134, 16, v176
	v_lshlrev_b32_e32 v135, 16, v192
	v_mov_b32_dpp v132, v132 quad_perm:[1,0,3,2] row_mask:0xf bank_mask:0xf bound_ctrl:1
	v_fmac_f32_e32 v132, v131, v131
	v_mov_b32_e32 v200, v136
	s_nop 0
	v_add_f32_dpp v132, v132, v132 quad_perm:[2,3,0,1] row_mask:0xf bank_mask:0xf bound_ctrl:1
	s_nop 1
	v_add_f32_dpp v132, v132, v132 row_half_mirror row_mask:0xf bank_mask:0xf bound_ctrl:1
	s_nop 1
	v_add_f32_dpp v132, v132, v132 row_mirror row_mask:0xf bank_mask:0xf bound_ctrl:1
	s_nop 0
	v_readlane_b32 s3, v132, 16
	v_readlane_b32 s25, v132, 48
	v_readlane_b32 s2, v132, 0
	v_readlane_b32 s24, v132, 32
	v_mov_b32_e32 v132, s3
	v_mov_b32_e32 v133, s25
	v_add_f32_e32 v132, s2, v132
	v_add_f32_e32 v133, s24, v133
	v_add_f32_e32 v132, v132, v133
	v_max_f32_e32 v132, 0x179abe15, v132
	v_rsq_f32_e32 v132, v132
	v_add_f32_e32 v133, -1.0, v134
	v_fma_f32 v133, v232, v133, 1.0
	v_mul_f32_e32 v130, v130, v133
	v_mul_f32_e32 v131, v131, v132
	v_mul_f32_e32 v132, v131, v134
	v_mul_f32_e32 v131, v131, v137
	v_mul_f32_e32 v137, v137, v184
	v_rcp_f32_e32 v133, v137
	s_nop 0
	v_mul_f32_e32 v132, v132, v133
	v_mul_f32_e32 v130, v130, v133
	ds_write2st64_b32 v129, v131, v132 offset0:1 offset1:2
	ds_write2st64_b32 v129, v130, v135 offset0:3 offset1:5
	v_lshlrev_b32_e32 v136, 16, v169
	v_sub_f32_e32 v130, v200, v136
	v_fma_f32 v130, v230, v130, v136
	v_mul_f32_e32 v131, v231, v130
	v_mul_f32_e32 v132, v131, v131
	v_lshlrev_b32_e32 v134, 16, v177
	v_lshlrev_b32_e32 v135, 16, v193
	v_mov_b32_dpp v132, v132 quad_perm:[1,0,3,2] row_mask:0xf bank_mask:0xf bound_ctrl:1
	v_fmac_f32_e32 v132, v131, v131
	v_mov_b32_e32 v200, v136
	s_nop 0
	v_add_f32_dpp v132, v132, v132 quad_perm:[2,3,0,1] row_mask:0xf bank_mask:0xf bound_ctrl:1
	s_nop 1
	v_add_f32_dpp v132, v132, v132 row_half_mirror row_mask:0xf bank_mask:0xf bound_ctrl:1
	s_nop 1
	v_add_f32_dpp v132, v132, v132 row_mirror row_mask:0xf bank_mask:0xf bound_ctrl:1
	s_nop 0
	v_readlane_b32 s3, v132, 16
; #define LAS __attribute__((address_space(3)))
; __device__ __forceinline__ float frsq(float x) { return __builtin_amdgcn_rsqf(x); }
; template <int MODE> __device__ __forceinline__ void rwkv_item(const Params& P, int e, int c, int h, LAS float* slab, int lane) {
;     ...
; #pragma unroll
;         for (int s = 0; s < SB; ++s) {
;             const float r = r1[s + 1] + (r1[s] - r1[s + 1]) * mu_r, k = k1[s + 1] + (k1[s] - k1[s + 1]) * mu_k, a = aa[s];
;             float kk = k * kkw;
;             const float ss = wave_sum(kk * kk);
;             kk *= frsq(fmaxf(ss, 1e-24f));
;             const float b = kk * a, kp = k * (1.f + (a - 1.f) * ka);
;             LAS float* st = slab + s * 512;
;             st[lane] = dd[s]; st[64 + lane] = kk; st[128 + lane] = b; st[192 + lane] = kp; st[256 + lane] = r; st[320 + lane] = vv[s];
	v_readlane_b32 s25, v132, 48
	v_readlane_b32 s2, v132, 0
	v_readlane_b32 s24, v132, 32
	v_mov_b32_e32 v132, s3
	v_mov_b32_e32 v133, s25
	v_add_f32_e32 v132, s2, v132
	v_add_f32_e32 v133, s24, v133
	v_add_f32_e32 v132, v132, v133
	v_max_f32_e32 v132, 0x179abe15, v132
	v_rsq_f32_e32 v132, v132
	v_add_f32_e32 v133, -1.0, v134
	v_fma_f32 v133, v232, v133, 1.0
	v_mul_f32_e32 v130, v130, v133
	v_mul_f32_e32 v131, v131, v132
	v_mul_f32_e32 v132, v131, v134
	v_mul_f32_e32 v131, v131, v137
	v_mul_f32_e32 v137, v137, v185
	v_rcp_f32_e32 v133, v137
	s_nop 0
	v_mul_f32_e32 v132, v132, v133
	v_mul_f32_e32 v130, v130, v133
	ds_write2st64_b32 v129, v131, v132 offset0:9 offset1:10
	ds_write2st64_b32 v129, v130, v135 offset0:11 offset1:13
	v_lshlrev_b32_e32 v136, 16, v170
	v_sub_f32_e32 v130, v200, v136
	v_fma_f32 v130, v230, v130, v136
	v_mul_f32_e32 v131, v231, v130
	v_mul_f32_e32 v132, v131, v131
	v_lshlrev_b32_e32 v134, 16, v178
	v_lshlrev_b32_e32 v135, 16, v194
	v_mov_b32_dpp v132, v132 quad_perm:[1,0,3,2] row_mask:0xf bank_mask:0xf bound_ctrl:1
	v_fmac_f32_e32 v132, v131, v131
	v_mov_b32_e32 v200, v136
	s_nop 0
	v_add_f32_dpp v132, v132, v132 quad_perm:[2,3,0,1] row_mask:0xf bank_mask:0xf bound_ctrl:1
	s_nop 1
	v_add_f32_dpp v132, v132, v132 row_half_mirror row_mask:0xf bank_mask:0xf bound_ctrl:1
	s_nop 1
	v_add_f32_dpp v132, v132, v132 row_mirror row_mask:0xf bank_mask:0xf bound_ctrl:1
	s_nop 0
	v_readlane_b32 s3, v132, 16
	v_readlane_b32 s25, v132, 48
	v_readlane_b32 s2, v132, 0
	v_readlane_b32 s24, v132, 32
	v_mov_b32_e32 v132, s3
	v_mov_b32_e32 v133, s25
	v_add_f32_e32 v132, s2, v132
	v_add_f32_e32 v133, s24, v133
	v_add_f32_e32 v132, v132, v133
	v_max_f32_e32 v132, 0x179abe15, v132
	v_rsq_f32_e32 v132, v132
	v_add_f32_e32 v133, -1.0, v134
	v_fma_f32 v133, v232, v133, 1.0
	v_mul_f32_e32 v130, v130, v133
	v_mul_f32_e32 v131, v131, v132
	v_mul_f32_e32 v132, v131, v134
	v_mul_f32_e32 v131, v131, v137
	v_mul_f32_e32 v137, v137, v186
	v_rcp_f32_e32 v133, v137
	s_nop 0
	v_mul_f32_e32 v132, v132, v133
	v_mul_f32_e32 v130, v130, v133
	ds_write2st64_b32 v129, v131, v132 offset0:17 offset1:18
	ds_write2st64_b32 v129, v130, v135 offset0:19 offset1:21
	v_lshlrev_b32_e32 v136, 16, v171
	v_sub_f32_e32 v130, v200, v136
	v_fma_f32 v130, v230, v130, v136
	v_mul_f32_e32 v131, v231, v130
	v_mul_f32_e32 v132, v131, v131
	v_lshlrev_b32_e32 v134, 16, v179
	v_lshlrev_b32_e32 v135, 16, v195
	v_mov_b32_dpp v132, v132 quad_perm:[1,0,3,2] row_mask:0xf bank_mask:0xf bound_ctrl:1
	v_fmac_f32_e32 v132, v131, v131
	v_mov_b32_e32 v200, v136
	s_nop 0
	v_add_f32_dpp v132, v132, v132 quad_perm:[2,3,0,1] row_mask:0xf bank_mask:0xf bound_ctrl:1
	s_nop 1
	v_add_f32_dpp v132, v132, v132 row_half_mirror row_mask:0xf bank_mask:0xf bound_ctrl:1
	s_nop 1
	v_add_f32_dpp v132, v132, v132 row_mirror row_mask:0xf bank_mask:0xf bound_ctrl:1
	s_nop 0
	v_readlane_b32 s3, v132, 16
	v_readlane_b32 s25, v132, 48
	v_readlane_b32 s2, v132, 0
	v_readlane_b32 s24, v132, 32
	v_mov_b32_e32 v132, s3
	v_mov_b32_e32 v133, s25
	v_add_f32_e32 v132, s2, v132
	v_add_f32_e32 v133, s24, v133
	v_add_f32_e32 v132, v132, v133
	v_max_f32_e32 v132, 0x179abe15, v132
	v_rsq_f32_e32 v132, v132
	v_add_f32_e32 v133, -1.0, v134
	v_fma_f32 v133, v232, v133, 1.0
	v_mul_f32_e32 v130, v130, v133
	v_mul_f32_e32 v131, v131, v132
	v_mul_f32_e32 v132, v131, v134
	v_mul_f32_e32 v131, v131, v137
	v_mul_f32_e32 v137, v137, v187
	v_rcp_f32_e32 v133, v137
	s_nop 0
	v_mul_f32_e32 v132, v132, v133
	v_mul_f32_e32 v130, v130, v133
	ds_write2st64_b32 v129, v131, v132 offset0:25 offset1:26
	ds_write2st64_b32 v129, v130, v135 offset0:27 offset1:29
	v_lshlrev_b32_e32 v136, 16, v172
	v_sub_f32_e32 v130, v200, v136
	v_fma_f32 v130, v230, v130, v136
	v_mul_f32_e32 v131, v231, v130
	v_mul_f32_e32 v132, v131, v131
	v_lshlrev_b32_e32 v134, 16, v180
	v_lshlrev_b32_e32 v135, 16, v196
	v_mov_b32_dpp v132, v132 quad_perm:[1,0,3,2] row_mask:0xf bank_mask:0xf bound_ctrl:1
	v_fmac_f32_e32 v132, v131, v131
	v_mov_b32_e32 v200, v136
	s_nop 0
	v_add_f32_dpp v132, v132, v132 quad_perm:[2,3,0,1] row_mask:0xf bank_mask:0xf bound_ctrl:1
	s_nop 1
	v_add_f32_dpp v132, v132, v132 row_half_mirror row_mask:0xf bank_mask:0xf bound_ctrl:1
	s_nop 1
	v_add_f32_dpp v132, v132, v132 row_mirror row_mask:0xf bank_mask:0xf bound_ctrl:1
	s_nop 0
	v_readlane_b32 s3, v132, 16
	v_readlane_b32 s25, v132, 48
	v_readlane_b32 s2, v132, 0
	v_readlane_b32 s24, v132, 32
	v_mov_b32_e32 v132, s3
	v_mov_b32_e32 v133, s25
	v_add_f32_e32 v132, s2, v132
	v_add_f32_e32 v133, s24, v133
	v_add_f32_e32 v132, v132, v133
	v_max_f32_e32 v132, 0x179abe15, v132
	v_rsq_f32_e32 v132, v132
	v_add_f32_e32 v133, -1.0, v134
	v_fma_f32 v133, v232, v133, 1.0
	v_mul_f32_e32 v130, v130, v133
	v_mul_f32_e32 v131, v131, v132
	v_mul_f32_e32 v132, v131, v134
	v_mul_f32_e32 v131, v131, v137
	v_mul_f32_e32 v137, v137, v188
	v_rcp_f32_e32 v133, v137
	s_nop 0
	v_mul_f32_e32 v132, v132, v133
	v_mul_f32_e32 v130, v130, v133
	ds_write2st64_b32 v129, v131, v132 offset0:33 offset1:34
	ds_write2st64_b32 v129, v130, v135 offset0:35 offset1:37
	v_lshlrev_b32_e32 v136, 16, v173
	v_sub_f32_e32 v130, v200, v136
	v_fma_f32 v130, v230, v130, v136
	v_mul_f32_e32 v131, v231, v130
	v_mul_f32_e32 v132, v131, v131
	v_lshlrev_b32_e32 v134, 16, v181
	v_lshlrev_b32_e32 v135, 16, v197
	v_mov_b32_dpp v132, v132 quad_perm:[1,0,3,2] row_mask:0xf bank_mask:0xf bound_ctrl:1
	v_fmac_f32_e32 v132, v131, v131
	v_mov_b32_e32 v200, v136
	s_nop 0
	v_add_f32_dpp v132, v132, v132 quad_perm:[2,3,0,1] row_mask:0xf bank_mask:0xf bound_ctrl:1
	s_nop 1
	v_add_f32_dpp v132, v132, v132 row_half_mirror row_mask:0xf bank_mask:0xf bound_ctrl:1
	s_nop 1
; #define LAS __attribute__((address_space(3)))
; __device__ __forceinline__ float frsq(float x) { return __builtin_amdgcn_rsqf(x); }
; template <int MODE> __device__ __forceinline__ void rwkv_item(const Params& P, int e, int c, int h, LAS float* slab, int lane) {
;     ...
; #pragma unroll
;         for (int s = 0; s < SB; ++s) {
;             const float r = r1[s + 1] + (r1[s] - r1[s + 1]) * mu_r, k = k1[s + 1] + (k1[s] - k1[s + 1]) * mu_k, a = aa[s];
;             float kk = k * kkw;
;             const float ss = wave_sum(kk * kk);
;             kk *= frsq(fmaxf(ss, 1e-24f));
;             const float b = kk * a, kp = k * (1.f + (a - 1.f) * ka);
;             LAS float* st = slab + s * 512;
;             st[lane] = dd[s]; st[64 + lane] = kk; st[128 + lane] = b; st[192 + lane] = kp; st[256 + lane] = r; st[320 + lane] = vv[s];
	v_add_f32_dpp v132, v132, v132 row_mirror row_mask:0xf bank_mask:0xf bound_ctrl:1
	s_nop 0
	v_readlane_b32 s3, v132, 16
	v_readlane_b32 s25, v132, 48
	v_readlane_b32 s2, v132, 0
	v_readlane_b32 s24, v132, 32
	v_mov_b32_e32 v132, s3
	v_mov_b32_e32 v133, s25
	v_add_f32_e32 v132, s2, v132
	v_add_f32_e32 v133, s24, v133
	v_add_f32_e32 v132, v132, v133
	v_max_f32_e32 v132, 0x179abe15, v132
	v_rsq_f32_e32 v132, v132
	v_add_f32_e32 v133, -1.0, v134
	v_fma_f32 v133, v232, v133, 1.0
	v_mul_f32_e32 v130, v130, v133
	v_mul_f32_e32 v131, v131, v132
	v_mul_f32_e32 v132, v131, v134
	v_mul_f32_e32 v131, v131, v137
	v_mul_f32_e32 v137, v137, v189
	v_rcp_f32_e32 v133, v137
	s_nop 0
	v_mul_f32_e32 v132, v132, v133
	v_mul_f32_e32 v130, v130, v133
	ds_write2st64_b32 v129, v131, v132 offset0:41 offset1:42
	ds_write2st64_b32 v129, v130, v135 offset0:43 offset1:45
	v_lshlrev_b32_e32 v136, 16, v174
	v_sub_f32_e32 v130, v200, v136
	v_fma_f32 v130, v230, v130, v136
	v_mul_f32_e32 v131, v231, v130
	v_mul_f32_e32 v132, v131, v131
	v_lshlrev_b32_e32 v134, 16, v182
	v_lshlrev_b32_e32 v135, 16, v198
	v_mov_b32_dpp v132, v132 quad_perm:[1,0,3,2] row_mask:0xf bank_mask:0xf bound_ctrl:1
	v_fmac_f32_e32 v132, v131, v131
	v_mov_b32_e32 v200, v136
	s_nop 0
	v_add_f32_dpp v132, v132, v132 quad_perm:[2,3,0,1] row_mask:0xf bank_mask:0xf bound_ctrl:1
	s_nop 1
	v_add_f32_dpp v132, v132, v132 row_half_mirror row_mask:0xf bank_mask:0xf bound_ctrl:1
	s_nop 1
	v_add_f32_dpp v132, v132, v132 row_mirror row_mask:0xf bank_mask:0xf bound_ctrl:1
	s_nop 0
	v_readlane_b32 s3, v132, 16
	v_readlane_b32 s25, v132, 48
	v_readlane_b32 s2, v132, 0
	v_readlane_b32 s24, v132, 32
	v_mov_b32_e32 v132, s3
	v_mov_b32_e32 v133, s25
	v_add_f32_e32 v132, s2, v132
	v_add_f32_e32 v133, s24, v133
	v_add_f32_e32 v132, v132, v133
	v_max_f32_e32 v132, 0x179abe15, v132
	v_rsq_f32_e32 v132, v132
	v_add_f32_e32 v133, -1.0, v134
	v_fma_f32 v133, v232, v133, 1.0
	v_mul_f32_e32 v130, v130, v133
	v_mul_f32_e32 v131, v131, v132
	v_mul_f32_e32 v132, v131, v134
	v_mul_f32_e32 v131, v131, v137
	v_mul_f32_e32 v137, v137, v190
	v_rcp_f32_e32 v133, v137
	s_nop 0
	v_mul_f32_e32 v132, v132, v133
	v_mul_f32_e32 v130, v130, v133
	ds_write2st64_b32 v129, v131, v132 offset0:49 offset1:50
	ds_write2st64_b32 v129, v130, v135 offset0:51 offset1:53
	v_lshlrev_b32_e32 v136, 16, v175
	v_sub_f32_e32 v130, v200, v136
	v_fma_f32 v130, v230, v130, v136
	v_mul_f32_e32 v131, v231, v130
	v_mul_f32_e32 v132, v131, v131
	v_lshlrev_b32_e32 v134, 16, v183
	v_lshlrev_b32_e32 v135, 16, v199
	v_mov_b32_dpp v132, v132 quad_perm:[1,0,3,2] row_mask:0xf bank_mask:0xf bound_ctrl:1
	v_fmac_f32_e32 v132, v131, v131
	v_mov_b32_e32 v200, v136
	s_nop 0
	v_add_f32_dpp v132, v132, v132 quad_perm:[2,3,0,1] row_mask:0xf bank_mask:0xf bound_ctrl:1
	s_nop 1
	v_add_f32_dpp v132, v132, v132 row_half_mirror row_mask:0xf bank_mask:0xf bound_ctrl:1
	s_nop 1
	v_add_f32_dpp v132, v132, v132 row_mirror row_mask:0xf bank_mask:0xf bound_ctrl:1
	s_nop 0
	v_readlane_b32 s3, v132, 16
	v_readlane_b32 s25, v132, 48
	v_readlane_b32 s2, v132, 0
	v_readlane_b32 s24, v132, 32
	v_mov_b32_e32 v132, s3
	v_mov_b32_e32 v133, s25
	v_add_f32_e32 v132, s2, v132
	v_add_f32_e32 v133, s24, v133
	v_add_f32_e32 v132, v132, v133
	v_max_f32_e32 v132, 0x179abe15, v132
	v_rsq_f32_e32 v132, v132
	v_add_f32_e32 v133, -1.0, v134
	v_fma_f32 v133, v232, v133, 1.0
	v_mul_f32_e32 v130, v130, v133
	v_mul_f32_e32 v131, v131, v132
	v_mul_f32_e32 v132, v131, v134
	v_mul_f32_e32 v131, v131, v137
	v_mul_f32_e32 v137, v137, v191
	v_rcp_f32_e32 v133, v137
	s_nop 0
	v_mul_f32_e32 v132, v132, v133
	v_mul_f32_e32 v130, v130, v133
	ds_write2st64_b32 v129, v131, v132 offset0:57 offset1:58
	ds_write2st64_b32 v129, v130, v135 offset0:59 offset1:61
	s_cmp_eq_u32 s23, 7
	s_cbranch_scc1 .Lm0_noload
	global_load_ushort v168, v201, s[26:27]
	global_load_ushort v169, v201, s[26:27] offset:3584
	v_add_u32_e32 v204, 0x1c00, v201
	v_add_u32_e32 v205, 0x3800, v201
	v_add_u32_e32 v206, 0x5400, v201
	global_load_ushort v170, v204, s[26:27]
	global_load_ushort v171, v204, s[26:27] offset:3584
	global_load_ushort v172, v205, s[26:27]
	global_load_ushort v173, v205, s[26:27] offset:3584
	global_load_ushort v174, v206, s[26:27]
	global_load_ushort v175, v206, s[26:27] offset:3584
	v_add_u32_e32 v204, 0x1000, v202
	global_load_ushort v176, v202, s[14:15]
	global_load_ushort v177, v202, s[14:15] offset:1024
	global_load_ushort v178, v202, s[14:15] offset:2048
	global_load_ushort v179, v202, s[14:15] offset:3072
	global_load_ushort v180, v204, s[14:15]
	global_load_ushort v181, v204, s[14:15] offset:1024
	global_load_ushort v182, v204, s[14:15] offset:2048
	global_load_ushort v183, v204, s[14:15] offset:3072
	global_load_ushort v192, v202, s[16:17]
	global_load_ushort v193, v202, s[16:17] offset:1024
	global_load_ushort v194, v202, s[16:17] offset:2048
	global_load_ushort v195, v202, s[16:17] offset:3072
	global_load_ushort v196, v204, s[16:17]
	global_load_ushort v197, v204, s[16:17] offset:1024
	global_load_ushort v198, v204, s[16:17] offset:2048
	global_load_ushort v199, v204, s[16:17] offset:3072
	v_add_u32_e32 v205, 0x1000, v203
	v_add_u32_e32 v206, 0x2000, v203
	v_add_u32_e32 v207, 0x3000, v203
	global_load_dword v184, v203, s[10:11]
	global_load_dword v185, v203, s[10:11] offset:2048
	global_load_dword v186, v205, s[10:11]
	global_load_dword v187, v205, s[10:11] offset:2048
	global_load_dword v188, v206, s[10:11]
	global_load_dword v189, v206, s[10:11] offset:2048
	global_load_dword v190, v207, s[10:11]
	global_load_dword v191, v207, s[10:11] offset:2048
	v_add_u32_e32 v201, 0x7000, v201
	v_add_u32_e32 v202, 0x2000, v202
	v_add_u32_e32 v203, 0x4000, v203

; #define LAS __attribute__((address_space(3)))
; #define RW_LD_DOT(buf, hb) do { _Pragma("unroll") for (int q_ = 0; q_ < DB; ++q_) kd[buf][q_] = *(const LAS f32x4*)(st + 64 + 4 * (DB * (hb) + q_)); } while (0)
; #define RW_LD_UPD(buf, qb) do { _Pragma("unroll") for (int q_ = 0; q_ < UB; ++q_) { const int qq_ = UB * (qb) + q_; \
;                 wq[buf][q_] = *(const LAS f32x4*)(st + 4 * qq_); bq[buf][q_] = *(const LAS f32x4*)(st + 128 + 4 * qq_); kq[buf][q_] = *(const LAS f32x4*)(st + 192 + 4 * qq_); \
;                 if (MODE == 1) rq[buf][q_] = *(const LAS f32x4*)(st + 256 + 4 * qq_); } } while (0)
; template <int MODE> __device__ __forceinline__ void rwkv_item(const Params& P, int e, int c, int h, LAS float* slab, int lane) {
;     ...
;         for (int s = 0; s < SB; ++s) {
;             const LAS float* st = slab + s * 512;
;             f32x2 aS0 = {0.f, 0.f}, aS1 = {0.f, 0.f}, aC0 = {0.f, 0.f}, aC1 = {0.f, 0.f};
;             constexpr int DB = 4, UB = 2;
;             constexpr int NDB = 16 / DB, NUB = 16 / UB;
;             constexpr int NB = MODE == 1 ? 2 : 1;
;             f32x4 kd[NB][DB];
;             f32x4 wq[NB][UB], bq[NB][UB], kq[NB][UB], rq[NB][MODE == 1 ? UB : 1];
;     ...
;             if (NB == 2) RW_LD_DOT(0, 0);
;             const float v = st[320 + lane];
; #pragma unroll
;             for (int hb = 0; hb < NDB; ++hb) {
;                 if (NB == 2) { if (hb + 1 < NDB) RW_LD_DOT((hb + 1) & 1, hb + 1); else RW_LD_UPD(0, 0); } else RW_LD_DOT(0, hb);
;                 __builtin_amdgcn_sched_barrier(0);
; #pragma unroll
;                 for (int q = 0; q < DB; ++q) {
;                     const int qq = DB * hb + q; const f32x4 k4 = kd[hb & (NB - 1)][q];
;                     aS0 += S2[2 * qq] * (f32x2){k4.x, k4.y}; aS1 += S2[2 * qq + 1] * (f32x2){k4.z, k4.w};
;                     if (MODE == 0) { aC0 += C2[2 * qq] * (f32x2){k4.x, k4.y}; aC1 += C2[2 * qq + 1] * (f32x2){k4.z, k4.w}; }
;                 }
;                 __builtin_amdgcn_sched_barrier(0);
;             }
;             const float nsk = -((aS0.x + aS0.y) + (aS1.x + aS1.y));
;             const float nskC = -((aC0.x + aC0.y) + (aC1.x + aC1.y));
.Lm0_step:
	v_add_u32_e32 v152, 0x500, v129
	s_add_i32 s3, s21, s2
	v_add_u32_e32 v152, s2, v152
	v_mov_b32_e32 v233, s3
	ds_read_b32 v152, v152
	ds_read_b128 v[214:217], v233 offset:256
	ds_read_b128 v[234:237], v233 offset:272
	ds_read_b128 v[238:241], v233 offset:288
	ds_read_b128 v[242:245], v233 offset:304
	ds_read_b128 v[246:249], v233 offset:320
	ds_read_b128 v[140:143], v233 offset:336
	ds_read_b128 v[144:147], v233 offset:352
	ds_read_b128 v[148:151], v233 offset:368
	s_waitcnt lgkmcnt(7)
	v_pk_fma_f32 v[158:159], v[112:113], v[214:215], 0 op_sel_hi:[1,1,0]
	v_pk_fma_f32 v[160:161], v[114:115], v[216:217], 0 op_sel_hi:[1,1,0]
	v_pk_fma_f32 v[162:163], v[124:125], v[214:215], 0 op_sel_hi:[1,1,0]
	v_pk_fma_f32 v[164:165], v[126:127], v[216:217], 0 op_sel_hi:[1,1,0]
	ds_read_b128 v[214:217], v233 offset:384
	s_waitcnt lgkmcnt(7)
	v_pk_fma_f32 v[158:159], v[104:105], v[234:235], v[158:159]
	v_pk_fma_f32 v[160:161], v[106:107], v[236:237], v[160:161]
	v_pk_fma_f32 v[162:163], v[120:121], v[234:235], v[162:163]
	v_pk_fma_f32 v[164:165], v[122:123], v[236:237], v[164:165]
	ds_read_b128 v[234:237], v233 offset:400
	s_waitcnt lgkmcnt(7)
	v_pk_fma_f32 v[158:159], v[92:93], v[238:239], v[158:159]
	v_pk_fma_f32 v[160:161], v[94:95], v[240:241], v[160:161]
	v_pk_fma_f32 v[162:163], v[116:117], v[238:239], v[162:163]
	v_pk_fma_f32 v[164:165], v[118:119], v[240:241], v[164:165]
	ds_read_b128 v[238:241], v233 offset:416
	s_waitcnt lgkmcnt(7)
	v_pk_fma_f32 v[158:159], v[76:77], v[242:243], v[158:159]
	v_pk_fma_f32 v[160:161], v[78:79], v[244:245], v[160:161]
	v_pk_fma_f32 v[162:163], v[108:109], v[242:243], v[162:163]
	v_pk_fma_f32 v[164:165], v[110:111], v[244:245], v[164:165]
	ds_read_b128 v[242:245], v233 offset:432
	s_waitcnt lgkmcnt(7)
	v_pk_fma_f32 v[158:159], v[64:65], v[246:247], v[158:159]
	v_pk_fma_f32 v[160:161], v[66:67], v[248:249], v[160:161]
	v_pk_fma_f32 v[162:163], v[96:97], v[246:247], v[162:163]
	v_pk_fma_f32 v[164:165], v[98:99], v[248:249], v[164:165]
	ds_read_b128 v[246:249], v233 offset:448
	s_waitcnt lgkmcnt(7)
	v_pk_fma_f32 v[158:159], v[100:101], v[140:141], v[158:159]
	v_pk_fma_f32 v[160:161], v[102:103], v[142:143], v[160:161]
	v_pk_fma_f32 v[162:163], v[80:81], v[140:141], v[162:163]
	v_pk_fma_f32 v[164:165], v[82:83], v[142:143], v[164:165]
	ds_read_b128 v[140:143], v233 offset:464
	s_waitcnt lgkmcnt(7)
	v_pk_fma_f32 v[158:159], v[88:89], v[144:145], v[158:159]
	v_pk_fma_f32 v[160:161], v[90:91], v[146:147], v[160:161]
	v_pk_fma_f32 v[162:163], v[68:69], v[144:145], v[162:163]
	v_pk_fma_f32 v[164:165], v[70:71], v[146:147], v[164:165]
	ds_read_b128 v[144:147], v233 offset:480
	s_waitcnt lgkmcnt(7)
	v_pk_fma_f32 v[158:159], v[84:85], v[148:149], v[158:159]
	v_pk_fma_f32 v[160:161], v[86:87], v[150:151], v[160:161]
	v_pk_fma_f32 v[162:163], v[52:53], v[148:149], v[162:163]
	v_pk_fma_f32 v[164:165], v[54:55], v[150:151], v[164:165]
	ds_read_b128 v[148:151], v233 offset:496
	s_waitcnt lgkmcnt(7)
	v_pk_fma_f32 v[158:159], v[72:73], v[214:215], v[158:159]
	v_pk_fma_f32 v[160:161], v[74:75], v[216:217], v[160:161]
	v_pk_fma_f32 v[162:163], v[44:45], v[214:215], v[162:163]
	v_pk_fma_f32 v[164:165], v[46:47], v[216:217], v[164:165]
	ds_read_b128 v[214:217], v233 offset:512
	s_waitcnt lgkmcnt(7)
	v_pk_fma_f32 v[158:159], v[60:61], v[234:235], v[158:159]
	v_pk_fma_f32 v[160:161], v[62:63], v[236:237], v[160:161]
	v_pk_fma_f32 v[162:163], v[32:33], v[234:235], v[162:163]
	v_pk_fma_f32 v[164:165], v[34:35], v[236:237], v[164:165]
	ds_read_b128 v[234:237], v233 offset:768
	s_waitcnt lgkmcnt(7)
	v_pk_fma_f32 v[158:159], v[56:57], v[238:239], v[158:159]
	v_pk_fma_f32 v[160:161], v[58:59], v[240:241], v[160:161]
	v_pk_fma_f32 v[162:163], v[24:25], v[238:239], v[162:163]
	v_pk_fma_f32 v[164:165], v[26:27], v[240:241], v[164:165]
	ds_read_b128 v[238:241], v233 offset:528
	s_waitcnt lgkmcnt(7)
	v_pk_fma_f32 v[158:159], v[48:49], v[242:243], v[158:159]
	v_pk_fma_f32 v[160:161], v[50:51], v[244:245], v[160:161]
	v_pk_fma_f32 v[162:163], v[16:17], v[242:243], v[162:163]
	v_pk_fma_f32 v[164:165], v[18:19], v[244:245], v[164:165]
	ds_read_b128 v[242:245], v233 offset:784
	s_waitcnt lgkmcnt(7)
	v_pk_fma_f32 v[158:159], v[40:41], v[246:247], v[158:159]
	v_pk_fma_f32 v[160:161], v[42:43], v[248:249], v[160:161]
	v_pk_fma_f32 v[162:163], v[12:13], v[246:247], v[162:163]
	v_pk_fma_f32 v[164:165], v[14:15], v[248:249], v[164:165]
	ds_read_b128 v[246:249], v233 offset:544
	s_waitcnt lgkmcnt(7)
	v_pk_fma_f32 v[158:159], v[36:37], v[140:141], v[158:159]
	v_pk_fma_f32 v[160:161], v[38:39], v[142:143], v[160:161]
	v_pk_fma_f32 v[162:163], v[8:9], v[140:141], v[162:163]
	v_pk_fma_f32 v[164:165], v[10:11], v[142:143], v[164:165]
	ds_read_b128 v[140:143], v233 offset:800
	s_waitcnt lgkmcnt(7)
	v_pk_fma_f32 v[158:159], v[28:29], v[144:145], v[158:159]
	v_pk_fma_f32 v[160:161], v[30:31], v[146:147], v[160:161]
	v_pk_fma_f32 v[162:163], v[4:5], v[144:145], v[162:163]
	v_pk_fma_f32 v[164:165], v[6:7], v[146:147], v[164:165]
	ds_read_b128 v[144:147], v233 offset:560
	s_waitcnt lgkmcnt(7)
	v_pk_fma_f32 v[158:159], v[20:21], v[148:149], v[158:159]
	v_pk_fma_f32 v[160:161], v[22:23], v[150:151], v[160:161]
	v_pk_fma_f32 v[162:163], v[0:1], v[148:149], v[162:163]
	v_pk_fma_f32 v[164:165], v[2:3], v[150:151], v[164:165]
	ds_read_b128 v[148:151], v233 offset:816
	v_add_f32_e32 v208, v158, v159
	v_add_f32_e32 v209, v160, v161
	v_add_f32_e32 v250, v162, v163
	v_add_f32_e32 v251, v164, v165
	v_add_f32_e32 v208, v209, v208
	v_add_f32_e32 v250, v251, v250
	s_waitcnt lgkmcnt(7)
; #define RW_LD_UPD(buf, qb) do { _Pragma("unroll") for (int q_ = 0; q_ < UB; ++q_) { const int qq_ = UB * (qb) + q_; \
;                 wq[buf][q_] = *(const LAS f32x4*)(st + 4 * qq_); bq[buf][q_] = *(const LAS f32x4*)(st + 128 + 4 * qq_); kq[buf][q_] = *(const LAS f32x4*)(st + 192 + 4 * qq_); \
;                 if (MODE == 1) rq[buf][q_] = *(const LAS f32x4*)(st + 256 + 4 * qq_); } } while (0)
; template <int MODE> __device__ __forceinline__ void rwkv_item(const Params& P, int e, int c, int h, LAS float* slab, int lane) {
;     ...
;             f32x2 y0 = {0.f, 0.f}, y1 = {0.f, 0.f};
; #pragma unroll
;             for (int qb = 0; qb < NUB; ++qb) {
;                 if (NB == 2) { if (qb + 1 < NUB) RW_LD_UPD((qb + 1) & 1, qb + 1); } else RW_LD_UPD(0, qb);
;                 __builtin_amdgcn_sched_barrier(0);
; #pragma unroll
;                 for (int q = 0; q < UB; ++q) {
;                     const int qq = UB * qb + q;
;                     const f32x4 w4 = wq[qb & (NB - 1)][q], b4 = bq[qb & (NB - 1)][q], k4 = kq[qb & (NB - 1)][q];
;                     if (MODE == 0) {
;                         S2[2 * qq] = S2[2 * qq] * (f32x2){w4.x, w4.y} + (f32x2){b4.x, b4.y} * nsk;
;                         S2[2 * qq + 1] = S2[2 * qq + 1] * (f32x2){w4.z, w4.w} + (f32x2){b4.z, b4.w} * nsk;
;                         C2[2 * qq] = C2[2 * qq] * (f32x2){w4.x, w4.y} + (f32x2){b4.x, b4.y} * nskC + (f32x2){k4.x, k4.y} * v;
;                         C2[2 * qq + 1] = C2[2 * qq + 1] * (f32x2){w4.z, w4.w} + (f32x2){b4.z, b4.w} * nskC + (f32x2){k4.z, k4.w} * v;
	v_pk_fma_f32 v[112:113], v[214:215], v[208:209], v[112:113] op_sel_hi:[1,0,1] neg_lo:[0,1,0] neg_hi:[0,1,0]
	v_pk_fma_f32 v[114:115], v[216:217], v[208:209], v[114:115] op_sel_hi:[1,0,1] neg_lo:[0,1,0] neg_hi:[0,1,0]
	v_pk_fma_f32 v[124:125], v[214:215], v[250:251], v[124:125] op_sel_hi:[1,0,1] neg_lo:[0,1,0] neg_hi:[0,1,0]
	v_pk_fma_f32 v[126:127], v[216:217], v[250:251], v[126:127] op_sel_hi:[1,0,1] neg_lo:[0,1,0] neg_hi:[0,1,0]
	ds_read_b128 v[214:217], v233 offset:576
	s_waitcnt lgkmcnt(7)
	v_pk_fma_f32 v[124:125], v[152:153], v[234:235], v[124:125] op_sel_hi:[0,1,1]
	v_pk_fma_f32 v[126:127], v[152:153], v[236:237], v[126:127] op_sel_hi:[0,1,1]
	ds_read_b128 v[234:237], v233 offset:832
	s_waitcnt lgkmcnt(7)
	v_pk_fma_f32 v[104:105], v[238:239], v[208:209], v[104:105] op_sel_hi:[1,0,1] neg_lo:[0,1,0] neg_hi:[0,1,0]
	v_pk_fma_f32 v[106:107], v[240:241], v[208:209], v[106:107] op_sel_hi:[1,0,1] neg_lo:[0,1,0] neg_hi:[0,1,0]
	v_pk_fma_f32 v[120:121], v[238:239], v[250:251], v[120:121] op_sel_hi:[1,0,1] neg_lo:[0,1,0] neg_hi:[0,1,0]
	v_pk_fma_f32 v[122:123], v[240:241], v[250:251], v[122:123] op_sel_hi:[1,0,1] neg_lo:[0,1,0] neg_hi:[0,1,0]
	ds_read_b128 v[238:241], v233 offset:592
	s_waitcnt lgkmcnt(7)
	v_pk_fma_f32 v[120:121], v[152:153], v[242:243], v[120:121] op_sel_hi:[0,1,1]
	v_pk_fma_f32 v[122:123], v[152:153], v[244:245], v[122:123] op_sel_hi:[0,1,1]
	ds_read_b128 v[242:245], v233 offset:848
	s_waitcnt lgkmcnt(7)
	v_pk_fma_f32 v[92:93], v[246:247], v[208:209], v[92:93] op_sel_hi:[1,0,1] neg_lo:[0,1,0] neg_hi:[0,1,0]
	v_pk_fma_f32 v[94:95], v[248:249], v[208:209], v[94:95] op_sel_hi:[1,0,1] neg_lo:[0,1,0] neg_hi:[0,1,0]
	v_pk_fma_f32 v[116:117], v[246:247], v[250:251], v[116:117] op_sel_hi:[1,0,1] neg_lo:[0,1,0] neg_hi:[0,1,0]
	v_pk_fma_f32 v[118:119], v[248:249], v[250:251], v[118:119] op_sel_hi:[1,0,1] neg_lo:[0,1,0] neg_hi:[0,1,0]
	ds_read_b128 v[246:249], v233 offset:608
	s_waitcnt lgkmcnt(7)
	v_pk_fma_f32 v[116:117], v[152:153], v[140:141], v[116:117] op_sel_hi:[0,1,1]
	v_pk_fma_f32 v[118:119], v[152:153], v[142:143], v[118:119] op_sel_hi:[0,1,1]
	ds_read_b128 v[140:143], v233 offset:864
	s_waitcnt lgkmcnt(7)
	v_pk_fma_f32 v[76:77], v[144:145], v[208:209], v[76:77] op_sel_hi:[1,0,1] neg_lo:[0,1,0] neg_hi:[0,1,0]
	v_pk_fma_f32 v[78:79], v[146:147], v[208:209], v[78:79] op_sel_hi:[1,0,1] neg_lo:[0,1,0] neg_hi:[0,1,0]
	v_pk_fma_f32 v[108:109], v[144:145], v[250:251], v[108:109] op_sel_hi:[1,0,1] neg_lo:[0,1,0] neg_hi:[0,1,0]
	v_pk_fma_f32 v[110:111], v[146:147], v[250:251], v[110:111] op_sel_hi:[1,0,1] neg_lo:[0,1,0] neg_hi:[0,1,0]
	ds_read_b128 v[144:147], v233 offset:624
	s_waitcnt lgkmcnt(7)
	v_pk_fma_f32 v[108:109], v[152:153], v[148:149], v[108:109] op_sel_hi:[0,1,1]
	v_pk_fma_f32 v[110:111], v[152:153], v[150:151], v[110:111] op_sel_hi:[0,1,1]
	ds_read_b128 v[148:151], v233 offset:880
	s_waitcnt lgkmcnt(7)
	v_pk_fma_f32 v[64:65], v[214:215], v[208:209], v[64:65] op_sel_hi:[1,0,1] neg_lo:[0,1,0] neg_hi:[0,1,0]
	v_pk_fma_f32 v[66:67], v[216:217], v[208:209], v[66:67] op_sel_hi:[1,0,1] neg_lo:[0,1,0] neg_hi:[0,1,0]
	v_pk_fma_f32 v[96:97], v[214:215], v[250:251], v[96:97] op_sel_hi:[1,0,1] neg_lo:[0,1,0] neg_hi:[0,1,0]
	v_pk_fma_f32 v[98:99], v[216:217], v[250:251], v[98:99] op_sel_hi:[1,0,1] neg_lo:[0,1,0] neg_hi:[0,1,0]
	ds_read_b128 v[214:217], v233 offset:640
	s_waitcnt lgkmcnt(7)
	v_pk_fma_f32 v[96:97], v[152:153], v[234:235], v[96:97] op_sel_hi:[0,1,1]
	v_pk_fma_f32 v[98:99], v[152:153], v[236:237], v[98:99] op_sel_hi:[0,1,1]
	ds_read_b128 v[234:237], v233 offset:896
	s_waitcnt lgkmcnt(7)
	v_pk_fma_f32 v[100:101], v[238:239], v[208:209], v[100:101] op_sel_hi:[1,0,1] neg_lo:[0,1,0] neg_hi:[0,1,0]
	v_pk_fma_f32 v[102:103], v[240:241], v[208:209], v[102:103] op_sel_hi:[1,0,1] neg_lo:[0,1,0] neg_hi:[0,1,0]
	v_pk_fma_f32 v[80:81], v[238:239], v[250:251], v[80:81] op_sel_hi:[1,0,1] neg_lo:[0,1,0] neg_hi:[0,1,0]
	v_pk_fma_f32 v[82:83], v[240:241], v[250:251], v[82:83] op_sel_hi:[1,0,1] neg_lo:[0,1,0] neg_hi:[0,1,0]
	ds_read_b128 v[238:241], v233 offset:656
	s_waitcnt lgkmcnt(7)
	v_pk_fma_f32 v[80:81], v[152:153], v[242:243], v[80:81] op_sel_hi:[0,1,1]
	v_pk_fma_f32 v[82:83], v[152:153], v[244:245], v[82:83] op_sel_hi:[0,1,1]
	ds_read_b128 v[242:245], v233 offset:912
	s_waitcnt lgkmcnt(7)
	v_pk_fma_f32 v[88:89], v[246:247], v[208:209], v[88:89] op_sel_hi:[1,0,1] neg_lo:[0,1,0] neg_hi:[0,1,0]
	v_pk_fma_f32 v[90:91], v[248:249], v[208:209], v[90:91] op_sel_hi:[1,0,1] neg_lo:[0,1,0] neg_hi:[0,1,0]
	v_pk_fma_f32 v[68:69], v[246:247], v[250:251], v[68:69] op_sel_hi:[1,0,1] neg_lo:[0,1,0] neg_hi:[0,1,0]
	v_pk_fma_f32 v[70:71], v[248:249], v[250:251], v[70:71] op_sel_hi:[1,0,1] neg_lo:[0,1,0] neg_hi:[0,1,0]
	ds_read_b128 v[246:249], v233 offset:672
	s_waitcnt lgkmcnt(7)
	v_pk_fma_f32 v[68:69], v[152:153], v[140:141], v[68:69] op_sel_hi:[0,1,1]
	v_pk_fma_f32 v[70:71], v[152:153], v[142:143], v[70:71] op_sel_hi:[0,1,1]
	ds_read_b128 v[140:143], v233 offset:928
	s_waitcnt lgkmcnt(7)
	v_pk_fma_f32 v[84:85], v[144:145], v[208:209], v[84:85] op_sel_hi:[1,0,1] neg_lo:[0,1,0] neg_hi:[0,1,0]
	v_pk_fma_f32 v[86:87], v[146:147], v[208:209], v[86:87] op_sel_hi:[1,0,1] neg_lo:[0,1,0] neg_hi:[0,1,0]
	v_pk_fma_f32 v[52:53], v[144:145], v[250:251], v[52:53] op_sel_hi:[1,0,1] neg_lo:[0,1,0] neg_hi:[0,1,0]
	v_pk_fma_f32 v[54:55], v[146:147], v[250:251], v[54:55] op_sel_hi:[1,0,1] neg_lo:[0,1,0] neg_hi:[0,1,0]
	ds_read_b128 v[144:147], v233 offset:688
	s_waitcnt lgkmcnt(7)
	v_pk_fma_f32 v[52:53], v[152:153], v[148:149], v[52:53] op_sel_hi:[0,1,1]
	v_pk_fma_f32 v[54:55], v[152:153], v[150:151], v[54:55] op_sel_hi:[0,1,1]
	ds_read_b128 v[148:151], v233 offset:944
	s_waitcnt lgkmcnt(7)
; #define LAS __attribute__((address_space(3)))
; __device__ __forceinline__ float frsq(float x) { return __builtin_amdgcn_rsqf(x); }
; #define LDS_WAIT() asm volatile("s_waitcnt lgkmcnt(0)" ::: "memory")
; template <int MODE> __device__ __forceinline__ void rwkv_item(const Params& P, int e, int c, int h, LAS float* slab, int lane) {
;     ...
;     for (int sb = 0; sb < RLCH / SB; ++sb) {
;         const int tb = c * RLCH + sb * SB;
;         if (MODE == 0) RW_LOAD(tb);
; #pragma unroll
;         for (int s = 0; s < SB; ++s) {
;             const float r = r1[s + 1] + (r1[s] - r1[s + 1]) * mu_r, k = k1[s + 1] + (k1[s] - k1[s + 1]) * mu_k, a = aa[s];
;             float kk = k * kkw;
;             const float ss = wave_sum(kk * kk);
;             kk *= frsq(fmaxf(ss, 1e-24f));
;             const float b = kk * a, kp = k * (1.f + (a - 1.f) * ka);
;             LAS float* st = slab + s * 512;
;             st[lane] = dd[s]; st[64 + lane] = kk; st[128 + lane] = b; st[192 + lane] = kp; st[256 + lane] = r; st[320 + lane] = vv[s];
;             if (MODE == 1) { st[384 + lane] = wave_sum(r * kp * rk); st[448 + lane] = gg[s]; }
;         }
;         LDS_WAIT();
;         if (MODE == 1 && sb + 1 < RLCH / SB) RW_LOAD(tb + SB);
; #pragma unroll 1
;         for (int s = 0; s < SB; ++s) {
;     ...
;             for (int qb = 0; qb < NUB; ++qb) {
;                 if (NB == 2) { if (qb + 1 < NUB) RW_LD_UPD((qb + 1) & 1, qb + 1); } else RW_LD_UPD(0, qb);
;                 __builtin_amdgcn_sched_barrier(0);
; #pragma unroll
;                 for (int q = 0; q < UB; ++q) {
;                     const int qq = UB * qb + q;
;                     const f32x4 w4 = wq[qb & (NB - 1)][q], b4 = bq[qb & (NB - 1)][q], k4 = kq[qb & (NB - 1)][q];
;                     if (MODE == 0) {
;                         S2[2 * qq] = S2[2 * qq] * (f32x2){w4.x, w4.y} + (f32x2){b4.x, b4.y} * nsk;
;                         S2[2 * qq + 1] = S2[2 * qq + 1] * (f32x2){w4.z, w4.w} + (f32x2){b4.z, b4.w} * nsk;
;                         C2[2 * qq] = C2[2 * qq] * (f32x2){w4.x, w4.y} + (f32x2){b4.x, b4.y} * nskC + (f32x2){k4.x, k4.y} * v;
;                         C2[2 * qq + 1] = C2[2 * qq + 1] * (f32x2){w4.z, w4.w} + (f32x2){b4.z, b4.w} * nskC + (f32x2){k4.z, k4.w} * v;
	v_pk_fma_f32 v[72:73], v[214:215], v[208:209], v[72:73] op_sel_hi:[1,0,1] neg_lo:[0,1,0] neg_hi:[0,1,0]
	v_pk_fma_f32 v[74:75], v[216:217], v[208:209], v[74:75] op_sel_hi:[1,0,1] neg_lo:[0,1,0] neg_hi:[0,1,0]
	v_pk_fma_f32 v[44:45], v[214:215], v[250:251], v[44:45] op_sel_hi:[1,0,1] neg_lo:[0,1,0] neg_hi:[0,1,0]
	v_pk_fma_f32 v[46:47], v[216:217], v[250:251], v[46:47] op_sel_hi:[1,0,1] neg_lo:[0,1,0] neg_hi:[0,1,0]
	ds_read_b128 v[214:217], v233 offset:704
	s_waitcnt lgkmcnt(7)
	v_pk_fma_f32 v[44:45], v[152:153], v[234:235], v[44:45] op_sel_hi:[0,1,1]
	v_pk_fma_f32 v[46:47], v[152:153], v[236:237], v[46:47] op_sel_hi:[0,1,1]
	ds_read_b128 v[234:237], v233 offset:960
	s_waitcnt lgkmcnt(7)
	v_pk_fma_f32 v[60:61], v[238:239], v[208:209], v[60:61] op_sel_hi:[1,0,1] neg_lo:[0,1,0] neg_hi:[0,1,0]
	v_pk_fma_f32 v[62:63], v[240:241], v[208:209], v[62:63] op_sel_hi:[1,0,1] neg_lo:[0,1,0] neg_hi:[0,1,0]
	v_pk_fma_f32 v[32:33], v[238:239], v[250:251], v[32:33] op_sel_hi:[1,0,1] neg_lo:[0,1,0] neg_hi:[0,1,0]
	v_pk_fma_f32 v[34:35], v[240:241], v[250:251], v[34:35] op_sel_hi:[1,0,1] neg_lo:[0,1,0] neg_hi:[0,1,0]
	ds_read_b128 v[238:241], v233 offset:720
	s_waitcnt lgkmcnt(7)
	v_pk_fma_f32 v[32:33], v[152:153], v[242:243], v[32:33] op_sel_hi:[0,1,1]
	v_pk_fma_f32 v[34:35], v[152:153], v[244:245], v[34:35] op_sel_hi:[0,1,1]
	ds_read_b128 v[242:245], v233 offset:976
	s_waitcnt lgkmcnt(7)
	v_pk_fma_f32 v[56:57], v[246:247], v[208:209], v[56:57] op_sel_hi:[1,0,1] neg_lo:[0,1,0] neg_hi:[0,1,0]
	v_pk_fma_f32 v[58:59], v[248:249], v[208:209], v[58:59] op_sel_hi:[1,0,1] neg_lo:[0,1,0] neg_hi:[0,1,0]
	v_pk_fma_f32 v[24:25], v[246:247], v[250:251], v[24:25] op_sel_hi:[1,0,1] neg_lo:[0,1,0] neg_hi:[0,1,0]
	v_pk_fma_f32 v[26:27], v[248:249], v[250:251], v[26:27] op_sel_hi:[1,0,1] neg_lo:[0,1,0] neg_hi:[0,1,0]
	ds_read_b128 v[246:249], v233 offset:736
	s_waitcnt lgkmcnt(7)
	v_pk_fma_f32 v[24:25], v[152:153], v[140:141], v[24:25] op_sel_hi:[0,1,1]
	v_pk_fma_f32 v[26:27], v[152:153], v[142:143], v[26:27] op_sel_hi:[0,1,1]
	ds_read_b128 v[140:143], v233 offset:992
	s_waitcnt lgkmcnt(7)
	v_pk_fma_f32 v[48:49], v[144:145], v[208:209], v[48:49] op_sel_hi:[1,0,1] neg_lo:[0,1,0] neg_hi:[0,1,0]
	v_pk_fma_f32 v[50:51], v[146:147], v[208:209], v[50:51] op_sel_hi:[1,0,1] neg_lo:[0,1,0] neg_hi:[0,1,0]
	v_pk_fma_f32 v[16:17], v[144:145], v[250:251], v[16:17] op_sel_hi:[1,0,1] neg_lo:[0,1,0] neg_hi:[0,1,0]
	v_pk_fma_f32 v[18:19], v[146:147], v[250:251], v[18:19] op_sel_hi:[1,0,1] neg_lo:[0,1,0] neg_hi:[0,1,0]
	ds_read_b128 v[144:147], v233 offset:752
	s_waitcnt lgkmcnt(7)
	v_pk_fma_f32 v[16:17], v[152:153], v[148:149], v[16:17] op_sel_hi:[0,1,1]
	v_pk_fma_f32 v[18:19], v[152:153], v[150:151], v[18:19] op_sel_hi:[0,1,1]
	ds_read_b128 v[148:151], v233 offset:1008
	s_waitcnt lgkmcnt(7)
	v_pk_fma_f32 v[40:41], v[214:215], v[208:209], v[40:41] op_sel_hi:[1,0,1] neg_lo:[0,1,0] neg_hi:[0,1,0]
	v_pk_fma_f32 v[42:43], v[216:217], v[208:209], v[42:43] op_sel_hi:[1,0,1] neg_lo:[0,1,0] neg_hi:[0,1,0]
	v_pk_fma_f32 v[12:13], v[214:215], v[250:251], v[12:13] op_sel_hi:[1,0,1] neg_lo:[0,1,0] neg_hi:[0,1,0]
	v_pk_fma_f32 v[14:15], v[216:217], v[250:251], v[14:15] op_sel_hi:[1,0,1] neg_lo:[0,1,0] neg_hi:[0,1,0]
	s_waitcnt lgkmcnt(6)
	v_pk_fma_f32 v[12:13], v[152:153], v[234:235], v[12:13] op_sel_hi:[0,1,1]
	v_pk_fma_f32 v[14:15], v[152:153], v[236:237], v[14:15] op_sel_hi:[0,1,1]
	s_waitcnt lgkmcnt(5)
	v_pk_fma_f32 v[36:37], v[238:239], v[208:209], v[36:37] op_sel_hi:[1,0,1] neg_lo:[0,1,0] neg_hi:[0,1,0]
	v_pk_fma_f32 v[38:39], v[240:241], v[208:209], v[38:39] op_sel_hi:[1,0,1] neg_lo:[0,1,0] neg_hi:[0,1,0]
	v_pk_fma_f32 v[8:9], v[238:239], v[250:251], v[8:9] op_sel_hi:[1,0,1] neg_lo:[0,1,0] neg_hi:[0,1,0]
	v_pk_fma_f32 v[10:11], v[240:241], v[250:251], v[10:11] op_sel_hi:[1,0,1] neg_lo:[0,1,0] neg_hi:[0,1,0]
	s_waitcnt lgkmcnt(4)
	v_pk_fma_f32 v[8:9], v[152:153], v[242:243], v[8:9] op_sel_hi:[0,1,1]
	v_pk_fma_f32 v[10:11], v[152:153], v[244:245], v[10:11] op_sel_hi:[0,1,1]
	s_waitcnt lgkmcnt(3)
	v_pk_fma_f32 v[28:29], v[246:247], v[208:209], v[28:29] op_sel_hi:[1,0,1] neg_lo:[0,1,0] neg_hi:[0,1,0]
	v_pk_fma_f32 v[30:31], v[248:249], v[208:209], v[30:31] op_sel_hi:[1,0,1] neg_lo:[0,1,0] neg_hi:[0,1,0]
	v_pk_fma_f32 v[4:5], v[246:247], v[250:251], v[4:5] op_sel_hi:[1,0,1] neg_lo:[0,1,0] neg_hi:[0,1,0]
	v_pk_fma_f32 v[6:7], v[248:249], v[250:251], v[6:7] op_sel_hi:[1,0,1] neg_lo:[0,1,0] neg_hi:[0,1,0]
	s_waitcnt lgkmcnt(2)
	v_pk_fma_f32 v[4:5], v[152:153], v[140:141], v[4:5] op_sel_hi:[0,1,1]
	v_pk_fma_f32 v[6:7], v[152:153], v[142:143], v[6:7] op_sel_hi:[0,1,1]
	s_waitcnt lgkmcnt(1)
	v_pk_fma_f32 v[20:21], v[144:145], v[208:209], v[20:21] op_sel_hi:[1,0,1] neg_lo:[0,1,0] neg_hi:[0,1,0]
	v_pk_fma_f32 v[22:23], v[146:147], v[208:209], v[22:23] op_sel_hi:[1,0,1] neg_lo:[0,1,0] neg_hi:[0,1,0]
	v_pk_fma_f32 v[0:1], v[144:145], v[250:251], v[0:1] op_sel_hi:[1,0,1] neg_lo:[0,1,0] neg_hi:[0,1,0]
	v_pk_fma_f32 v[2:3], v[146:147], v[250:251], v[2:3] op_sel_hi:[1,0,1] neg_lo:[0,1,0] neg_hi:[0,1,0]
	s_waitcnt lgkmcnt(0)
	v_pk_fma_f32 v[0:1], v[152:153], v[148:149], v[0:1] op_sel_hi:[0,1,1]
	v_pk_fma_f32 v[2:3], v[152:153], v[150:151], v[2:3] op_sel_hi:[0,1,1]
	s_addk_i32 s2, 0x800
	s_cmpk_eq_i32 s2, 0x4000
	s_cbranch_scc0 .Lm0_step
	s_add_i32 s23, s23, 1
	s_cmp_eq_u32 s23, 8
	s_cbranch_scc0 .Lm0_sub
; template <int MODE> __device__ __forceinline__ void rwkv_item(const Params& P, int e, int c, int h, LAS float* slab, int lane) {
;     ...
;     if (MODE == 0) {
; #pragma unroll
;         for (int q = 0; q < 16; ++q) {
;             *(f32x4*)(MCM + rowoff + 4 * q) = (f32x4){S2[2 * q].x, S2[2 * q].y, S2[2 * q + 1].x, S2[2 * q + 1].y};
;             *(f32x4*)(MCC + rowoff + 4 * q) = (f32x4){C2[2 * q].x, C2[2 * q].y, C2[2 * q + 1].x, C2[2 * q + 1].y};
;         }
;     }
; template <int MODE> __device__ __forceinline__ void stage_rwkv_scan(const Params& P, int e, LAS unsigned char* lds) {
;     ...
;     for (int it = gw; it < RNCH * 8; it += ngw) rwkv_item<MODE>(P, e, it >> 3, it & 7, slab, lane);
	ds_write_b32 v129, v137
	v_mov_b32_e32 v233, s21
	s_waitcnt lgkmcnt(0)
	ds_read_b128 v[214:217], v233
	ds_read_b128 v[234:237], v233 offset:16
	ds_read_b128 v[238:241], v233 offset:32
	ds_read_b128 v[242:245], v233 offset:48
	s_waitcnt lgkmcnt(3)
	v_pk_mul_f32 v[112:113], v[112:113], v[214:215]
	v_pk_mul_f32 v[114:115], v[114:115], v[216:217]
	v_pk_mul_f32 v[124:125], v[124:125], v[214:215]
	v_pk_mul_f32 v[126:127], v[126:127], v[216:217]
	s_waitcnt lgkmcnt(2)
	v_pk_mul_f32 v[104:105], v[104:105], v[234:235]
	v_pk_mul_f32 v[106:107], v[106:107], v[236:237]
	v_pk_mul_f32 v[120:121], v[120:121], v[234:235]
	v_pk_mul_f32 v[122:123], v[122:123], v[236:237]
	s_waitcnt lgkmcnt(1)
	v_pk_mul_f32 v[92:93], v[92:93], v[238:239]
	v_pk_mul_f32 v[94:95], v[94:95], v[240:241]
	v_pk_mul_f32 v[116:117], v[116:117], v[238:239]
	v_pk_mul_f32 v[118:119], v[118:119], v[240:241]
	s_waitcnt lgkmcnt(0)
	v_pk_mul_f32 v[76:77], v[76:77], v[242:243]
	v_pk_mul_f32 v[78:79], v[78:79], v[244:245]
	v_pk_mul_f32 v[108:109], v[108:109], v[242:243]
	v_pk_mul_f32 v[110:111], v[110:111], v[244:245]
	ds_read_b128 v[214:217], v233 offset:64
	ds_read_b128 v[234:237], v233 offset:80
	ds_read_b128 v[238:241], v233 offset:96
	ds_read_b128 v[242:245], v233 offset:112
	s_waitcnt lgkmcnt(3)
	v_pk_mul_f32 v[64:65], v[64:65], v[214:215]
	v_pk_mul_f32 v[66:67], v[66:67], v[216:217]
	v_pk_mul_f32 v[96:97], v[96:97], v[214:215]
	v_pk_mul_f32 v[98:99], v[98:99], v[216:217]
	s_waitcnt lgkmcnt(2)
	v_pk_mul_f32 v[100:101], v[100:101], v[234:235]
	v_pk_mul_f32 v[102:103], v[102:103], v[236:237]
	v_pk_mul_f32 v[80:81], v[80:81], v[234:235]
	v_pk_mul_f32 v[82:83], v[82:83], v[236:237]
	s_waitcnt lgkmcnt(1)
	v_pk_mul_f32 v[88:89], v[88:89], v[238:239]
	v_pk_mul_f32 v[90:91], v[90:91], v[240:241]
	v_pk_mul_f32 v[68:69], v[68:69], v[238:239]
	v_pk_mul_f32 v[70:71], v[70:71], v[240:241]
	s_waitcnt lgkmcnt(0)
	v_pk_mul_f32 v[84:85], v[84:85], v[242:243]
	v_pk_mul_f32 v[86:87], v[86:87], v[244:245]
	v_pk_mul_f32 v[52:53], v[52:53], v[242:243]
	v_pk_mul_f32 v[54:55], v[54:55], v[244:245]
	ds_read_b128 v[214:217], v233 offset:128
	ds_read_b128 v[234:237], v233 offset:144
	ds_read_b128 v[238:241], v233 offset:160
	ds_read_b128 v[242:245], v233 offset:176
	s_waitcnt lgkmcnt(3)
	v_pk_mul_f32 v[72:73], v[72:73], v[214:215]
	v_pk_mul_f32 v[74:75], v[74:75], v[216:217]
	v_pk_mul_f32 v[44:45], v[44:45], v[214:215]
	v_pk_mul_f32 v[46:47], v[46:47], v[216:217]
	s_waitcnt lgkmcnt(2)
	v_pk_mul_f32 v[60:61], v[60:61], v[234:235]
	v_pk_mul_f32 v[62:63], v[62:63], v[236:237]
	v_pk_mul_f32 v[32:33], v[32:33], v[234:235]
	v_pk_mul_f32 v[34:35], v[34:35], v[236:237]
	s_waitcnt lgkmcnt(1)
	v_pk_mul_f32 v[56:57], v[56:57], v[238:239]
	v_pk_mul_f32 v[58:59], v[58:59], v[240:241]
	v_pk_mul_f32 v[24:25], v[24:25], v[238:239]
	v_pk_mul_f32 v[26:27], v[26:27], v[240:241]
	s_waitcnt lgkmcnt(0)
	v_pk_mul_f32 v[48:49], v[48:49], v[242:243]
	v_pk_mul_f32 v[50:51], v[50:51], v[244:245]
	v_pk_mul_f32 v[16:17], v[16:17], v[242:243]
	v_pk_mul_f32 v[18:19], v[18:19], v[244:245]
	ds_read_b128 v[214:217], v233 offset:192
	ds_read_b128 v[234:237], v233 offset:208
	ds_read_b128 v[238:241], v233 offset:224
	ds_read_b128 v[242:245], v233 offset:240
	s_waitcnt lgkmcnt(3)
	v_pk_mul_f32 v[40:41], v[40:41], v[214:215]
	v_pk_mul_f32 v[42:43], v[42:43], v[216:217]
	v_pk_mul_f32 v[12:13], v[12:13], v[214:215]
	v_pk_mul_f32 v[14:15], v[14:15], v[216:217]
	s_waitcnt lgkmcnt(2)
	v_pk_mul_f32 v[36:37], v[36:37], v[234:235]
	v_pk_mul_f32 v[38:39], v[38:39], v[236:237]
	v_pk_mul_f32 v[8:9], v[8:9], v[234:235]
	v_pk_mul_f32 v[10:11], v[10:11], v[236:237]
	s_waitcnt lgkmcnt(1)
	v_pk_mul_f32 v[28:29], v[28:29], v[238:239]
	v_pk_mul_f32 v[30:31], v[30:31], v[240:241]
	v_pk_mul_f32 v[4:5], v[4:5], v[238:239]
	v_pk_mul_f32 v[6:7], v[6:7], v[240:241]
	s_waitcnt lgkmcnt(0)
	v_pk_mul_f32 v[20:21], v[20:21], v[242:243]
	v_pk_mul_f32 v[22:23], v[22:23], v[244:245]
	v_pk_mul_f32 v[0:1], v[0:1], v[242:243]
	v_pk_mul_f32 v[2:3], v[2:3], v[244:245]
	s_lshl_b32 s2, s20, 6
	v_or_b32_e32 v204, s2, v128
	v_lshlrev_b32_e32 v204, 8, v204
	s_add_i32 s20, s20, s58
	global_store_dwordx4 v204, v[112:115], s[18:19]
	global_store_dwordx4 v204, v[124:127], s[8:9]
	global_store_dwordx4 v204, v[104:107], s[18:19] offset:16
	global_store_dwordx4 v204, v[120:123], s[8:9] offset:16
	global_store_dwordx4 v204, v[92:95], s[18:19] offset:32
	global_store_dwordx4 v204, v[116:119], s[8:9] offset:32
	global_store_dwordx4 v204, v[76:79], s[18:19] offset:48
	global_store_dwordx4 v204, v[108:111], s[8:9] offset:48
	global_store_dwordx4 v204, v[64:67], s[18:19] offset:64
	global_store_dwordx4 v204, v[96:99], s[8:9] offset:64
	global_store_dwordx4 v204, v[100:103], s[18:19] offset:80
	global_store_dwordx4 v204, v[80:83], s[8:9] offset:80
	global_store_dwordx4 v204, v[88:91], s[18:19] offset:96
	global_store_dwordx4 v204, v[68:71], s[8:9] offset:96
	global_store_dwordx4 v204, v[84:87], s[18:19] offset:112
	global_store_dwordx4 v204, v[52:55], s[8:9] offset:112
	global_store_dwordx4 v204, v[72:75], s[18:19] offset:128
	global_store_dwordx4 v204, v[44:47], s[8:9] offset:128
	global_store_dwordx4 v204, v[60:63], s[18:19] offset:144
	global_store_dwordx4 v204, v[32:35], s[8:9] offset:144
	global_store_dwordx4 v204, v[56:59], s[18:19] offset:160
	global_store_dwordx4 v204, v[24:27], s[8:9] offset:160
	global_store_dwordx4 v204, v[48:51], s[18:19] offset:176
	global_store_dwordx4 v204, v[16:19], s[8:9] offset:176
	global_store_dwordx4 v204, v[40:43], s[18:19] offset:192
	global_store_dwordx4 v204, v[12:15], s[8:9] offset:192
	global_store_dwordx4 v204, v[36:39], s[18:19] offset:208
	global_store_dwordx4 v204, v[8:11], s[8:9] offset:208
	global_store_dwordx4 v204, v[28:31], s[18:19] offset:224
	global_store_dwordx4 v204, v[4:7], s[8:9] offset:224
	global_store_dwordx4 v204, v[20:23], s[18:19] offset:240
	global_store_dwordx4 v204, v[0:3], s[8:9] offset:240
	s_cmpk_gt_i32 s20, 0x7ff
	s_cbranch_scc0 .LBB0_262
	v_mov_b32_e32 v210, 1
	v_mov_b64_e32 v[244:245], 0x180
	v_mov_b64_e32 v[246:247], 0x80
	v_mov_b64_e32 v[248:249], 0x7f
